# static s_setprio raise for waves 4-7 in all seven GEMM K loops, per-phase flips removed
# baseline (speedup 1.0000x reference)
.LBB0_703:
	s_add_u32 s22, s22, 0x80080
	s_addc_u32 s23, s23, 0
	s_add_u32 s5, s24, 0x100
	v_mov_b32_e32 v2, 0
	s_addc_u32 s15, s25, 0
	s_mov_b32 s45, -2
	v_mov_b32_e32 v3, v2
	v_mov_b32_e32 v4, v2
	v_mov_b32_e32 v5, v2
	v_mov_b32_e32 v6, v2
	v_mov_b32_e32 v7, v2
	v_mov_b32_e32 v8, v2
	v_mov_b32_e32 v9, v2
	v_mov_b32_e32 v18, v2
	v_mov_b32_e32 v19, v2
	v_mov_b32_e32 v20, v2
	v_mov_b32_e32 v21, v2
	v_mov_b32_e32 v22, v2
	v_mov_b32_e32 v23, v2
	v_mov_b32_e32 v24, v2
	v_mov_b32_e32 v25, v2
	v_mov_b32_e32 v34, v2
	v_mov_b32_e32 v35, v2
	v_mov_b32_e32 v36, v2
	v_mov_b32_e32 v37, v2
	v_mov_b32_e32 v38, v2
	v_mov_b32_e32 v39, v2
	v_mov_b32_e32 v40, v2
	v_mov_b32_e32 v41, v2
	v_mov_b32_e32 v50, v2
	v_mov_b32_e32 v51, v2
	v_mov_b32_e32 v52, v2
	v_mov_b32_e32 v53, v2
	v_mov_b32_e32 v54, v2
	v_mov_b32_e32 v55, v2
	v_mov_b32_e32 v56, v2
	v_mov_b32_e32 v57, v2
	v_mov_b32_e32 v10, v2
	v_mov_b32_e32 v11, v2
	v_mov_b32_e32 v12, v2
	v_mov_b32_e32 v13, v2
	v_mov_b32_e32 v14, v2
	v_mov_b32_e32 v15, v2
	v_mov_b32_e32 v16, v2
	v_mov_b32_e32 v17, v2
	v_mov_b32_e32 v26, v2
	v_mov_b32_e32 v27, v2
	v_mov_b32_e32 v28, v2
	v_mov_b32_e32 v29, v2
	v_mov_b32_e32 v30, v2
	v_mov_b32_e32 v31, v2
	v_mov_b32_e32 v32, v2
	v_mov_b32_e32 v33, v2
	v_mov_b32_e32 v42, v2
	v_mov_b32_e32 v43, v2
	v_mov_b32_e32 v44, v2
	v_mov_b32_e32 v45, v2
	v_mov_b32_e32 v46, v2
	v_mov_b32_e32 v47, v2
	v_mov_b32_e32 v48, v2
	v_mov_b32_e32 v49, v2
	v_mov_b32_e32 v58, v2
	v_mov_b32_e32 v59, v2
	v_mov_b32_e32 v60, v2
	v_mov_b32_e32 v61, v2
	v_mov_b32_e32 v62, v2
	v_mov_b32_e32 v63, v2
	v_mov_b32_e32 v64, v2
	v_mov_b32_e32 v65, v2
	v_mov_b32_e32 v66, v2
	v_mov_b32_e32 v67, v2
	v_mov_b32_e32 v68, v2
	v_mov_b32_e32 v69, v2
	v_mov_b32_e32 v70, v2
	v_mov_b32_e32 v71, v2
	v_mov_b32_e32 v72, v2
	v_mov_b32_e32 v73, v2
	v_mov_b32_e32 v82, v2
	v_mov_b32_e32 v83, v2
	v_mov_b32_e32 v84, v2
	v_mov_b32_e32 v85, v2
	v_mov_b32_e32 v86, v2
	v_mov_b32_e32 v87, v2
	v_mov_b32_e32 v88, v2
	v_mov_b32_e32 v89, v2
	v_mov_b32_e32 v98, v2
	v_mov_b32_e32 v99, v2
	v_mov_b32_e32 v100, v2
	v_mov_b32_e32 v101, v2
	v_mov_b32_e32 v102, v2
	v_mov_b32_e32 v103, v2
	v_mov_b32_e32 v104, v2
	v_mov_b32_e32 v105, v2
	v_mov_b32_e32 v114, v2
	v_mov_b32_e32 v115, v2
	v_mov_b32_e32 v116, v2
	v_mov_b32_e32 v117, v2
	v_mov_b32_e32 v118, v2
	v_mov_b32_e32 v119, v2
	v_mov_b32_e32 v120, v2
	v_mov_b32_e32 v121, v2
	v_mov_b32_e32 v74, v2
	v_mov_b32_e32 v75, v2
	v_mov_b32_e32 v76, v2
	v_mov_b32_e32 v77, v2
	v_mov_b32_e32 v78, v2
	v_mov_b32_e32 v79, v2
	v_mov_b32_e32 v80, v2
	v_mov_b32_e32 v81, v2
	v_mov_b32_e32 v90, v2
	v_mov_b32_e32 v91, v2
	v_mov_b32_e32 v92, v2
	v_mov_b32_e32 v93, v2
	v_mov_b32_e32 v94, v2
	v_mov_b32_e32 v95, v2
	v_mov_b32_e32 v96, v2
	v_mov_b32_e32 v97, v2
	v_mov_b32_e32 v106, v2
	v_mov_b32_e32 v107, v2
	v_mov_b32_e32 v108, v2
	v_mov_b32_e32 v109, v2
	v_mov_b32_e32 v110, v2
	v_mov_b32_e32 v111, v2
	v_mov_b32_e32 v112, v2
	v_mov_b32_e32 v113, v2
	v_mov_b32_e32 v122, v2
	v_mov_b32_e32 v123, v2
	v_mov_b32_e32 v124, v2
	v_mov_b32_e32 v125, v2
	v_mov_b32_e32 v126, v2
	v_mov_b32_e32 v127, v2
	v_mov_b32_e32 v128, v2
	v_mov_b32_e32 v129, v2
	s_and_b64 s[98:99], exec, s[12:13]
	s_cbranch_scc1 .Lsp_p4
	s_setprio 1
.Lsp_p4:
.LBB0_704:
	ds_read_b128 v[144:147], v152
	ds_read_b128 v[156:159], v152 offset:1024
	ds_read_b128 v[160:163], v152 offset:2048
	ds_read_b128 v[166:169], v152 offset:3072
	ds_read_b128 v[170:173], v153
	ds_read_b128 v[174:177], v153 offset:1024
	ds_read_b128 v[178:181], v153 offset:2048
	ds_read_b128 v[182:185], v153 offset:3072
	s_add_u32 s24, s22, 0xfff80080
	s_addc_u32 s25, s23, -1
	s_cmp_eq_u32 s45, 28
	s_cselect_b32 s27, s17, s25
	s_cselect_b32 s26, s16, s24
	s_cselect_b32 s25, s21, s15
	s_cselect_b32 s24, s20, s5
	s_mov_b32 m0, s42
	v_lshl_add_u64 v[218:219], s[22:23], 0, v[140:141]
	ds_read_b128 v[186:189], v154
	ds_read_b128 v[190:193], v154 offset:1024
	ds_read_b128 v[194:197], v154 offset:2048
	ds_read_b128 v[198:201], v154 offset:3072
	ds_read_b128 v[202:205], v154 offset:4096
	ds_read_b128 v[206:209], v154 offset:5120
	ds_read_b128 v[210:213], v154 offset:6144
	ds_read_b128 v[214:217], v154 offset:7168
	global_load_lds_dwordx4 v[218:219], off
	v_lshl_add_u64 v[218:219], s[22:23], 0, v[142:143]
	s_add_i32 m0, s30, 0xe000
	s_nop 0
	global_load_lds_dwordx4 v[218:219], off
	s_waitcnt vmcnt(8)
	s_waitcnt lgkmcnt(0)
	s_barrier
	s_nop 0
	s_waitcnt lgkmcnt(0)
	v_mfma_f32_16x16x32_bf16 v[126:129], v[144:147], v[186:189], v[126:129]
	v_mfma_f32_16x16x32_bf16 v[122:125], v[160:163], v[186:189], v[122:125]
	v_mfma_f32_16x16x32_bf16 v[110:113], v[144:147], v[194:197], v[110:113]
	v_mfma_f32_16x16x32_bf16 v[106:109], v[160:163], v[194:197], v[106:109]
	v_mfma_f32_16x16x32_bf16 v[94:97], v[144:147], v[202:205], v[94:97]
	v_mfma_f32_16x16x32_bf16 v[90:93], v[160:163], v[202:205], v[90:93]
	v_mfma_f32_16x16x32_bf16 v[78:81], v[144:147], v[210:213], v[78:81]
	v_mfma_f32_16x16x32_bf16 v[74:77], v[160:163], v[210:213], v[74:77]
	v_mfma_f32_16x16x32_bf16 v[126:129], v[156:159], v[190:193], v[126:129]
	v_mfma_f32_16x16x32_bf16 v[122:125], v[166:169], v[190:193], v[122:125]
	v_mfma_f32_16x16x32_bf16 v[110:113], v[156:159], v[198:201], v[110:113]
	v_mfma_f32_16x16x32_bf16 v[106:109], v[166:169], v[198:201], v[106:109]
	v_mfma_f32_16x16x32_bf16 v[94:97], v[156:159], v[206:209], v[94:97]
	v_mfma_f32_16x16x32_bf16 v[90:93], v[166:169], v[206:209], v[90:93]
	v_mfma_f32_16x16x32_bf16 v[78:81], v[156:159], v[214:217], v[78:81]
	v_mfma_f32_16x16x32_bf16 v[74:77], v[166:169], v[214:217], v[74:77]
	s_nop 0
	s_nop 0
	v_mfma_f32_16x16x32_bf16 v[118:121], v[170:173], v[186:189], v[118:121]
	v_mfma_f32_16x16x32_bf16 v[114:117], v[178:181], v[186:189], v[114:117]
	v_mfma_f32_16x16x32_bf16 v[102:105], v[170:173], v[194:197], v[102:105]
	v_mfma_f32_16x16x32_bf16 v[98:101], v[178:181], v[194:197], v[98:101]
	v_mfma_f32_16x16x32_bf16 v[86:89], v[170:173], v[202:205], v[86:89]
	v_mfma_f32_16x16x32_bf16 v[82:85], v[178:181], v[202:205], v[82:85]
	v_mfma_f32_16x16x32_bf16 v[70:73], v[170:173], v[210:213], v[70:73]
	v_mfma_f32_16x16x32_bf16 v[66:69], v[178:181], v[210:213], v[66:69]
	v_mfma_f32_16x16x32_bf16 v[118:121], v[174:177], v[190:193], v[118:121]
	v_mfma_f32_16x16x32_bf16 v[114:117], v[182:185], v[190:193], v[114:117]
	v_mfma_f32_16x16x32_bf16 v[102:105], v[174:177], v[198:201], v[102:105]
	v_mfma_f32_16x16x32_bf16 v[98:101], v[182:185], v[198:201], v[98:101]
	v_mfma_f32_16x16x32_bf16 v[86:89], v[174:177], v[206:209], v[86:89]
	v_mfma_f32_16x16x32_bf16 v[82:85], v[182:185], v[206:209], v[82:85]
	v_mfma_f32_16x16x32_bf16 v[70:73], v[174:177], v[214:217], v[70:73]
	v_mfma_f32_16x16x32_bf16 v[66:69], v[182:185], v[214:217], v[66:69]
	s_nop 0
	s_barrier
	s_add_i32 s46, s40, s29
	v_lshl_add_u64 v[218:219], s[24:25], 0, v[134:135]
	s_mov_b32 m0, s46
	ds_read_b128 v[186:189], v154 offset:16384
	ds_read_b128 v[190:193], v154 offset:17408
	ds_read_b128 v[194:197], v154 offset:18432
	ds_read_b128 v[198:201], v154 offset:19456
	ds_read_b128 v[202:205], v154 offset:20480
	ds_read_b128 v[206:209], v154 offset:21504
	ds_read_b128 v[210:213], v154 offset:22528
	ds_read_b128 v[214:217], v154 offset:23552
	global_load_lds_dwordx4 v[218:219], off
	s_add_i32 m0, s46, 0x2000
	s_add_u32 s46, s24, 0x80000
	v_lshl_add_u64 v[220:221], s[24:25], 0, v[138:139]
	s_addc_u32 s47, s25, 0
	s_add_i32 s48, s41, s29
	global_load_lds_dwordx4 v[220:221], off
	v_lshl_add_u64 v[222:223], s[46:47], 0, v[134:135]
	s_mov_b32 m0, s48
	v_lshl_add_u64 v[224:225], s[26:27], 0, v[136:137]
	global_load_lds_dwordx4 v[222:223], off
	v_lshl_add_u64 v[222:223], s[46:47], 0, v[138:139]
	s_add_i32 m0, s48, 0x2000
	s_nop 0
	global_load_lds_dwordx4 v[222:223], off
	v_lshl_add_u64 v[222:223], s[26:27], 0, v[132:133]
	s_mov_b32 m0, s30
	s_nop 0
	global_load_lds_dwordx4 v[222:223], off
	s_mov_b32 m0, s31
	s_nop 0
	global_load_lds_dwordx4 v[224:225], off
	s_waitcnt vmcnt(8)
	s_waitcnt lgkmcnt(0)
	s_barrier
	s_nop 0
	s_waitcnt lgkmcnt(0)
	v_mfma_f32_16x16x32_bf16 v[62:65], v[144:147], v[186:189], v[62:65]
	v_mfma_f32_16x16x32_bf16 v[58:61], v[160:163], v[186:189], v[58:61]
	v_mfma_f32_16x16x32_bf16 v[46:49], v[144:147], v[194:197], v[46:49]
	v_mfma_f32_16x16x32_bf16 v[42:45], v[160:163], v[194:197], v[42:45]
	v_mfma_f32_16x16x32_bf16 v[30:33], v[144:147], v[202:205], v[30:33]
	v_mfma_f32_16x16x32_bf16 v[26:29], v[160:163], v[202:205], v[26:29]
	v_mfma_f32_16x16x32_bf16 v[14:17], v[144:147], v[210:213], v[14:17]
	v_mfma_f32_16x16x32_bf16 v[10:13], v[160:163], v[210:213], v[10:13]
	v_mfma_f32_16x16x32_bf16 v[62:65], v[156:159], v[190:193], v[62:65]
	v_mfma_f32_16x16x32_bf16 v[58:61], v[166:169], v[190:193], v[58:61]
	v_mfma_f32_16x16x32_bf16 v[46:49], v[156:159], v[198:201], v[46:49]
	v_mfma_f32_16x16x32_bf16 v[42:45], v[166:169], v[198:201], v[42:45]
	v_mfma_f32_16x16x32_bf16 v[30:33], v[156:159], v[206:209], v[30:33]
	v_mfma_f32_16x16x32_bf16 v[26:29], v[166:169], v[206:209], v[26:29]
	v_mfma_f32_16x16x32_bf16 v[14:17], v[156:159], v[214:217], v[14:17]
	v_mfma_f32_16x16x32_bf16 v[10:13], v[166:169], v[214:217], v[10:13]
	s_nop 0
	s_nop 0
	v_mfma_f32_16x16x32_bf16 v[54:57], v[170:173], v[186:189], v[54:57]
	v_mfma_f32_16x16x32_bf16 v[50:53], v[178:181], v[186:189], v[50:53]
	v_mfma_f32_16x16x32_bf16 v[38:41], v[170:173], v[194:197], v[38:41]
	v_mfma_f32_16x16x32_bf16 v[34:37], v[178:181], v[194:197], v[34:37]
	v_mfma_f32_16x16x32_bf16 v[22:25], v[170:173], v[202:205], v[22:25]
	v_mfma_f32_16x16x32_bf16 v[18:21], v[178:181], v[202:205], v[18:21]
	v_mfma_f32_16x16x32_bf16 v[6:9], v[170:173], v[210:213], v[6:9]
	v_mfma_f32_16x16x32_bf16 v[2:5], v[178:181], v[210:213], v[2:5]
	v_mfma_f32_16x16x32_bf16 v[54:57], v[174:177], v[190:193], v[54:57]
	v_mfma_f32_16x16x32_bf16 v[50:53], v[182:185], v[190:193], v[50:53]
	v_mfma_f32_16x16x32_bf16 v[38:41], v[174:177], v[198:201], v[38:41]
	v_mfma_f32_16x16x32_bf16 v[34:37], v[182:185], v[198:201], v[34:37]
	v_mfma_f32_16x16x32_bf16 v[22:25], v[174:177], v[206:209], v[22:25]
	v_mfma_f32_16x16x32_bf16 v[18:21], v[182:185], v[206:209], v[18:21]
	v_mfma_f32_16x16x32_bf16 v[6:9], v[174:177], v[214:217], v[6:9]
	v_mfma_f32_16x16x32_bf16 v[2:5], v[182:185], v[214:217], v[2:5]
	s_nop 0
	s_barrier
	s_add_i32 s46, 0, 0x18000
	v_add_u32_e32 v155, s46, v1
	s_add_i32 s47, 0, 0x1c000
	ds_read_b128 v[144:147], v155
	ds_read_b128 v[156:159], v155 offset:1024
	ds_read_b128 v[160:163], v155 offset:2048
	ds_read_b128 v[166:169], v155 offset:3072
	v_add_u32_e32 v155, s47, v1
	ds_read_b128 v[170:173], v155
	ds_read_b128 v[174:177], v155 offset:1024
	ds_read_b128 v[178:181], v155 offset:2048
	ds_read_b128 v[182:185], v155 offset:3072
	s_add_u32 s26, s26, 0x80000
	s_addc_u32 s27, s27, 0
	s_mov_b32 m0, s33
	v_lshl_add_u64 v[226:227], s[26:27], 0, v[132:133]
	ds_read_b128 v[186:189], v154 offset:32768
	ds_read_b128 v[190:193], v154 offset:33792
	ds_read_b128 v[194:197], v154 offset:34816
	ds_read_b128 v[198:201], v154 offset:35840
	ds_read_b128 v[202:205], v154 offset:36864
	ds_read_b128 v[206:209], v154 offset:37888
	ds_read_b128 v[210:213], v154 offset:38912
	ds_read_b128 v[214:217], v154 offset:39936
	global_load_lds_dwordx4 v[226:227], off
	v_lshl_add_u64 v[226:227], s[26:27], 0, v[136:137]
	s_mov_b32 m0, s34
	s_nop 0
	global_load_lds_dwordx4 v[226:227], off
	s_waitcnt vmcnt(8)
	s_waitcnt lgkmcnt(0)
	s_barrier
	s_nop 0
	s_waitcnt lgkmcnt(0)
	v_mfma_f32_16x16x32_bf16 v[126:129], v[144:147], v[186:189], v[126:129]
	v_mfma_f32_16x16x32_bf16 v[122:125], v[160:163], v[186:189], v[122:125]
	v_mfma_f32_16x16x32_bf16 v[110:113], v[144:147], v[194:197], v[110:113]
	v_mfma_f32_16x16x32_bf16 v[106:109], v[160:163], v[194:197], v[106:109]
	v_mfma_f32_16x16x32_bf16 v[94:97], v[144:147], v[202:205], v[94:97]
	v_mfma_f32_16x16x32_bf16 v[90:93], v[160:163], v[202:205], v[90:93]
	v_mfma_f32_16x16x32_bf16 v[78:81], v[144:147], v[210:213], v[78:81]
	v_mfma_f32_16x16x32_bf16 v[74:77], v[160:163], v[210:213], v[74:77]
	v_mfma_f32_16x16x32_bf16 v[126:129], v[156:159], v[190:193], v[126:129]
	v_mfma_f32_16x16x32_bf16 v[122:125], v[166:169], v[190:193], v[122:125]
	v_mfma_f32_16x16x32_bf16 v[110:113], v[156:159], v[198:201], v[110:113]
	v_mfma_f32_16x16x32_bf16 v[106:109], v[166:169], v[198:201], v[106:109]
	v_mfma_f32_16x16x32_bf16 v[94:97], v[156:159], v[206:209], v[94:97]
	v_mfma_f32_16x16x32_bf16 v[90:93], v[166:169], v[206:209], v[90:93]
	v_mfma_f32_16x16x32_bf16 v[78:81], v[156:159], v[214:217], v[78:81]
	v_mfma_f32_16x16x32_bf16 v[74:77], v[166:169], v[214:217], v[74:77]
	s_nop 0
	s_nop 0
	v_mfma_f32_16x16x32_bf16 v[118:121], v[170:173], v[186:189], v[118:121]
	v_mfma_f32_16x16x32_bf16 v[114:117], v[178:181], v[186:189], v[114:117]
	v_mfma_f32_16x16x32_bf16 v[102:105], v[170:173], v[194:197], v[102:105]
	v_mfma_f32_16x16x32_bf16 v[98:101], v[178:181], v[194:197], v[98:101]
	v_mfma_f32_16x16x32_bf16 v[86:89], v[170:173], v[202:205], v[86:89]
	v_mfma_f32_16x16x32_bf16 v[82:85], v[178:181], v[202:205], v[82:85]
	v_mfma_f32_16x16x32_bf16 v[70:73], v[170:173], v[210:213], v[70:73]
	v_mfma_f32_16x16x32_bf16 v[66:69], v[178:181], v[210:213], v[66:69]
	v_mfma_f32_16x16x32_bf16 v[118:121], v[174:177], v[190:193], v[118:121]
	v_mfma_f32_16x16x32_bf16 v[114:117], v[182:185], v[190:193], v[114:117]
	v_mfma_f32_16x16x32_bf16 v[102:105], v[174:177], v[198:201], v[102:105]
	v_mfma_f32_16x16x32_bf16 v[98:101], v[182:185], v[198:201], v[98:101]
	v_mfma_f32_16x16x32_bf16 v[86:89], v[174:177], v[206:209], v[86:89]
	v_mfma_f32_16x16x32_bf16 v[82:85], v[182:185], v[206:209], v[82:85]
	v_mfma_f32_16x16x32_bf16 v[70:73], v[174:177], v[214:217], v[70:73]
	v_mfma_f32_16x16x32_bf16 v[66:69], v[182:185], v[214:217], v[66:69]
	s_nop 0
	s_barrier
	s_add_i32 s26, s46, s29
	v_lshl_add_u64 v[218:219], v[218:219], 0, s[10:11]
	s_mov_b32 m0, s26
	ds_read_b128 v[186:189], v154 offset:49152
	ds_read_b128 v[190:193], v154 offset:50176
	ds_read_b128 v[194:197], v154 offset:51200
	ds_read_b128 v[198:201], v154 offset:52224
	ds_read_b128 v[202:205], v154 offset:53248
	ds_read_b128 v[206:209], v154 offset:54272
	ds_read_b128 v[210:213], v154 offset:55296
	ds_read_b128 v[214:217], v154 offset:56320
	global_load_lds_dwordx4 v[218:219], off
	s_add_i32 m0, s26, 0x2000
	s_add_u32 s24, s24, 0x80080
	v_lshl_add_u64 v[218:219], v[220:221], 0, s[10:11]
	s_addc_u32 s25, s25, 0
	s_add_i32 s26, s47, s29
	global_load_lds_dwordx4 v[218:219], off
	v_lshl_add_u64 v[218:219], s[24:25], 0, v[134:135]
	s_mov_b32 m0, s26
	s_nop 0
	global_load_lds_dwordx4 v[218:219], off
	v_lshl_add_u64 v[218:219], s[24:25], 0, v[138:139]
	s_add_i32 m0, s26, 0x2000
	s_nop 0
	global_load_lds_dwordx4 v[218:219], off
	v_lshl_add_u64 v[218:219], v[222:223], 0, s[10:11]
	s_mov_b32 m0, s38
	s_nop 0
	global_load_lds_dwordx4 v[218:219], off
	v_lshl_add_u64 v[218:219], v[224:225], 0, s[10:11]
	s_mov_b32 m0, s39
	s_nop 0
	global_load_lds_dwordx4 v[218:219], off
	s_waitcnt vmcnt(8)
	s_waitcnt lgkmcnt(0)
	s_barrier
	s_nop 0
	s_waitcnt lgkmcnt(0)
	v_mfma_f32_16x16x32_bf16 v[62:65], v[144:147], v[186:189], v[62:65]
	v_mfma_f32_16x16x32_bf16 v[58:61], v[160:163], v[186:189], v[58:61]
	v_mfma_f32_16x16x32_bf16 v[46:49], v[144:147], v[194:197], v[46:49]
	v_mfma_f32_16x16x32_bf16 v[42:45], v[160:163], v[194:197], v[42:45]
	v_mfma_f32_16x16x32_bf16 v[30:33], v[144:147], v[202:205], v[30:33]
	v_mfma_f32_16x16x32_bf16 v[26:29], v[160:163], v[202:205], v[26:29]
	v_mfma_f32_16x16x32_bf16 v[14:17], v[144:147], v[210:213], v[14:17]
	v_mfma_f32_16x16x32_bf16 v[10:13], v[160:163], v[210:213], v[10:13]
	v_mfma_f32_16x16x32_bf16 v[62:65], v[156:159], v[190:193], v[62:65]
	v_mfma_f32_16x16x32_bf16 v[58:61], v[166:169], v[190:193], v[58:61]
	v_mfma_f32_16x16x32_bf16 v[46:49], v[156:159], v[198:201], v[46:49]
	v_mfma_f32_16x16x32_bf16 v[42:45], v[166:169], v[198:201], v[42:45]
	v_mfma_f32_16x16x32_bf16 v[30:33], v[156:159], v[206:209], v[30:33]
	v_mfma_f32_16x16x32_bf16 v[26:29], v[166:169], v[206:209], v[26:29]
	v_mfma_f32_16x16x32_bf16 v[14:17], v[156:159], v[214:217], v[14:17]
	v_mfma_f32_16x16x32_bf16 v[10:13], v[166:169], v[214:217], v[10:13]
	s_nop 0
	s_nop 0
	v_mfma_f32_16x16x32_bf16 v[54:57], v[170:173], v[186:189], v[54:57]
	v_mfma_f32_16x16x32_bf16 v[50:53], v[178:181], v[186:189], v[50:53]
	v_mfma_f32_16x16x32_bf16 v[38:41], v[170:173], v[194:197], v[38:41]
	v_mfma_f32_16x16x32_bf16 v[34:37], v[178:181], v[194:197], v[34:37]
	v_mfma_f32_16x16x32_bf16 v[22:25], v[170:173], v[202:205], v[22:25]
	v_mfma_f32_16x16x32_bf16 v[18:21], v[178:181], v[202:205], v[18:21]
	v_mfma_f32_16x16x32_bf16 v[6:9], v[170:173], v[210:213], v[6:9]
	v_mfma_f32_16x16x32_bf16 v[2:5], v[178:181], v[210:213], v[2:5]
	v_mfma_f32_16x16x32_bf16 v[54:57], v[174:177], v[190:193], v[54:57]
	v_mfma_f32_16x16x32_bf16 v[50:53], v[182:185], v[190:193], v[50:53]
	v_mfma_f32_16x16x32_bf16 v[38:41], v[174:177], v[198:201], v[38:41]
	v_mfma_f32_16x16x32_bf16 v[34:37], v[182:185], v[198:201], v[34:37]
	v_mfma_f32_16x16x32_bf16 v[22:25], v[174:177], v[206:209], v[22:25]
	v_mfma_f32_16x16x32_bf16 v[18:21], v[182:185], v[206:209], v[18:21]
	v_mfma_f32_16x16x32_bf16 v[6:9], v[174:177], v[214:217], v[6:9]
	v_mfma_f32_16x16x32_bf16 v[2:5], v[182:185], v[214:217], v[2:5]
	s_nop 0
	s_barrier
	s_add_i32 s45, s45, 2
	s_add_u32 s22, s22, 0x100
	s_addc_u32 s23, s23, 0
	s_add_u32 s5, s5, 0x100
	s_addc_u32 s15, s15, 0
	s_cmp_gt_u32 s45, 29
	s_cbranch_scc0 .LBB0_704
	s_setprio 0
	s_and_b64 vcc, exec, s[12:13]
	s_cbranch_vccz .LBB0_707
	s_barrier

.LBB0_841:
	s_add_i32 s46, s45, -2
	s_add_u32 s4, s4, 0x60080
	s_addc_u32 s5, s5, 0
	s_add_u32 s47, s20, 0x100
	s_addc_u32 s48, s21, 0
	s_mov_b32 s20, 0
	s_and_b64 s[98:99], exec, s[10:11]
	s_cbranch_scc1 .Lsp_p5
	s_setprio 1
.Lsp_p5:
.LBB0_842:
	v_add_u32_e32 v158, s36, v152
	v_add_u32_e32 v162, s37, v152
	ds_read_b128 v[142:145], v158
	ds_read_b128 v[146:149], v158 offset:1024
	ds_read_b128 v[154:157], v158 offset:2048
	ds_read_b128 v[158:161], v158 offset:3072
	ds_read_b128 v[166:169], v162
	ds_read_b128 v[170:173], v162 offset:1024
	ds_read_b128 v[174:177], v162 offset:2048
	ds_read_b128 v[178:181], v162 offset:3072
	s_add_i32 s49, s20, 2
	s_add_u32 s21, s4, 0xfffa0080
	s_addc_u32 s22, s5, -1
	s_cmp_eq_u32 s46, s20
	s_cselect_b32 s20, s16, s47
	s_cselect_b32 s23, s15, s22
	s_cselect_b32 s22, s14, s21
	s_cselect_b32 s21, s17, s48
	v_lshl_add_u64 v[162:163], s[4:5], 0, v[138:139]
	s_add_i32 m0, s26, 0xc000
	ds_read_b128 v[182:185], v153
	ds_read_b128 v[186:189], v153 offset:1024
	ds_read_b128 v[190:193], v153 offset:2048
	ds_read_b128 v[194:197], v153 offset:3072
	ds_read_b128 v[198:201], v153 offset:4096
	ds_read_b128 v[202:205], v153 offset:5120
	ds_read_b128 v[206:209], v153 offset:6144
	ds_read_b128 v[210:213], v153 offset:7168
	global_load_lds_dwordx4 v[162:163], off
	v_lshl_add_u64 v[162:163], s[4:5], 0, v[140:141]
	s_add_i32 m0, s26, 0xe000
	s_nop 0
	global_load_lds_dwordx4 v[162:163], off
	s_waitcnt vmcnt(8)
	s_waitcnt lgkmcnt(0)
	s_barrier
	s_nop 0
	s_waitcnt lgkmcnt(0)
	v_mfma_f32_16x16x32_bf16 v[126:129], v[142:145], v[182:185], v[126:129]
	v_mfma_f32_16x16x32_bf16 v[122:125], v[154:157], v[182:185], v[122:125]
	v_mfma_f32_16x16x32_bf16 v[118:121], v[142:145], v[190:193], v[118:121]
	v_mfma_f32_16x16x32_bf16 v[114:117], v[154:157], v[190:193], v[114:117]
	v_mfma_f32_16x16x32_bf16 v[110:113], v[142:145], v[198:201], v[110:113]
	v_mfma_f32_16x16x32_bf16 v[106:109], v[154:157], v[198:201], v[106:109]
	v_mfma_f32_16x16x32_bf16 v[102:105], v[142:145], v[206:209], v[102:105]
	v_mfma_f32_16x16x32_bf16 v[98:101], v[154:157], v[206:209], v[98:101]
	v_mfma_f32_16x16x32_bf16 v[126:129], v[146:149], v[186:189], v[126:129]
	v_mfma_f32_16x16x32_bf16 v[122:125], v[158:161], v[186:189], v[122:125]
	v_mfma_f32_16x16x32_bf16 v[118:121], v[146:149], v[194:197], v[118:121]
	v_mfma_f32_16x16x32_bf16 v[114:117], v[158:161], v[194:197], v[114:117]
	v_mfma_f32_16x16x32_bf16 v[110:113], v[146:149], v[202:205], v[110:113]
	v_mfma_f32_16x16x32_bf16 v[106:109], v[158:161], v[202:205], v[106:109]
	v_mfma_f32_16x16x32_bf16 v[102:105], v[146:149], v[210:213], v[102:105]
	v_mfma_f32_16x16x32_bf16 v[98:101], v[158:161], v[210:213], v[98:101]
	s_nop 0
	s_nop 0
	v_mfma_f32_16x16x32_bf16 v[94:97], v[166:169], v[182:185], v[94:97]
	v_mfma_f32_16x16x32_bf16 v[90:93], v[174:177], v[182:185], v[90:93]
	v_mfma_f32_16x16x32_bf16 v[86:89], v[166:169], v[190:193], v[86:89]
	v_mfma_f32_16x16x32_bf16 v[82:85], v[174:177], v[190:193], v[82:85]
	v_mfma_f32_16x16x32_bf16 v[78:81], v[166:169], v[198:201], v[78:81]
	v_mfma_f32_16x16x32_bf16 v[74:77], v[174:177], v[198:201], v[74:77]
	v_mfma_f32_16x16x32_bf16 v[70:73], v[166:169], v[206:209], v[70:73]
	v_mfma_f32_16x16x32_bf16 v[66:69], v[174:177], v[206:209], v[66:69]
	v_mfma_f32_16x16x32_bf16 v[94:97], v[170:173], v[186:189], v[94:97]
	v_mfma_f32_16x16x32_bf16 v[90:93], v[178:181], v[186:189], v[90:93]
	v_mfma_f32_16x16x32_bf16 v[86:89], v[170:173], v[194:197], v[86:89]
	v_mfma_f32_16x16x32_bf16 v[82:85], v[178:181], v[194:197], v[82:85]
	v_mfma_f32_16x16x32_bf16 v[78:81], v[170:173], v[202:205], v[78:81]
	v_mfma_f32_16x16x32_bf16 v[74:77], v[178:181], v[202:205], v[74:77]
	v_mfma_f32_16x16x32_bf16 v[70:73], v[170:173], v[210:213], v[70:73]
	v_mfma_f32_16x16x32_bf16 v[66:69], v[178:181], v[210:213], v[66:69]
	s_nop 0
	s_barrier
	s_add_i32 s50, s36, s25
	v_lshl_add_u64 v[162:163], s[20:21], 0, v[132:133]
	s_mov_b32 m0, s50
	ds_read_b128 v[182:185], v153 offset:16384
	ds_read_b128 v[186:189], v153 offset:17408
	ds_read_b128 v[190:193], v153 offset:18432
	ds_read_b128 v[194:197], v153 offset:19456
	ds_read_b128 v[198:201], v153 offset:20480
	ds_read_b128 v[202:205], v153 offset:21504
	ds_read_b128 v[206:209], v153 offset:22528
	ds_read_b128 v[210:213], v153 offset:23552
	global_load_lds_dwordx4 v[162:163], off
	s_add_i32 m0, s50, 0x2000
	s_add_u32 s50, s20, 0x60000
	v_lshl_add_u64 v[214:215], s[20:21], 0, v[136:137]
	s_addc_u32 s51, s21, 0
	s_add_i32 s52, s37, s25
	global_load_lds_dwordx4 v[214:215], off
	v_lshl_add_u64 v[216:217], s[50:51], 0, v[132:133]
	s_mov_b32 m0, s52
	v_lshl_add_u64 v[218:219], s[22:23], 0, v[134:135]
	global_load_lds_dwordx4 v[216:217], off
	v_lshl_add_u64 v[216:217], s[50:51], 0, v[136:137]
	s_add_i32 m0, s52, 0x2000
	s_nop 0
	global_load_lds_dwordx4 v[216:217], off
	v_lshl_add_u64 v[216:217], s[22:23], 0, v[130:131]
	s_mov_b32 m0, s26
	s_nop 0
	global_load_lds_dwordx4 v[216:217], off
	s_mov_b32 m0, s27
	s_nop 0
	global_load_lds_dwordx4 v[218:219], off
	s_waitcnt vmcnt(8)
	s_waitcnt lgkmcnt(0)
	s_barrier
	s_nop 0
	s_waitcnt lgkmcnt(0)
	v_mfma_f32_16x16x32_bf16 v[62:65], v[142:145], v[182:185], v[62:65]
	v_mfma_f32_16x16x32_bf16 v[58:61], v[154:157], v[182:185], v[58:61]
	v_mfma_f32_16x16x32_bf16 v[54:57], v[142:145], v[190:193], v[54:57]
	v_mfma_f32_16x16x32_bf16 v[50:53], v[154:157], v[190:193], v[50:53]
	v_mfma_f32_16x16x32_bf16 v[46:49], v[142:145], v[198:201], v[46:49]
	v_mfma_f32_16x16x32_bf16 v[42:45], v[154:157], v[198:201], v[42:45]
	v_mfma_f32_16x16x32_bf16 v[38:41], v[142:145], v[206:209], v[38:41]
	v_mfma_f32_16x16x32_bf16 v[34:37], v[154:157], v[206:209], v[34:37]
	v_mfma_f32_16x16x32_bf16 v[62:65], v[146:149], v[186:189], v[62:65]
	v_mfma_f32_16x16x32_bf16 v[58:61], v[158:161], v[186:189], v[58:61]
	v_mfma_f32_16x16x32_bf16 v[54:57], v[146:149], v[194:197], v[54:57]
	v_mfma_f32_16x16x32_bf16 v[50:53], v[158:161], v[194:197], v[50:53]
	v_mfma_f32_16x16x32_bf16 v[46:49], v[146:149], v[202:205], v[46:49]
	v_mfma_f32_16x16x32_bf16 v[42:45], v[158:161], v[202:205], v[42:45]
	v_mfma_f32_16x16x32_bf16 v[38:41], v[146:149], v[210:213], v[38:41]
	v_mfma_f32_16x16x32_bf16 v[34:37], v[158:161], v[210:213], v[34:37]
	s_nop 0
	s_nop 0
	v_mfma_f32_16x16x32_bf16 v[30:33], v[166:169], v[182:185], v[30:33]
	v_mfma_f32_16x16x32_bf16 v[26:29], v[174:177], v[182:185], v[26:29]
	v_mfma_f32_16x16x32_bf16 v[22:25], v[166:169], v[190:193], v[22:25]
	v_mfma_f32_16x16x32_bf16 v[18:21], v[174:177], v[190:193], v[18:21]
	v_mfma_f32_16x16x32_bf16 v[14:17], v[166:169], v[198:201], v[14:17]
	v_mfma_f32_16x16x32_bf16 v[10:13], v[174:177], v[198:201], v[10:13]
	v_mfma_f32_16x16x32_bf16 v[6:9], v[166:169], v[206:209], v[6:9]
	v_mfma_f32_16x16x32_bf16 v[2:5], v[174:177], v[206:209], v[2:5]
	v_mfma_f32_16x16x32_bf16 v[30:33], v[170:173], v[186:189], v[30:33]
	v_mfma_f32_16x16x32_bf16 v[26:29], v[178:181], v[186:189], v[26:29]
	v_mfma_f32_16x16x32_bf16 v[22:25], v[170:173], v[194:197], v[22:25]
	v_mfma_f32_16x16x32_bf16 v[18:21], v[178:181], v[194:197], v[18:21]
	v_mfma_f32_16x16x32_bf16 v[14:17], v[170:173], v[202:205], v[14:17]
	v_mfma_f32_16x16x32_bf16 v[10:13], v[178:181], v[202:205], v[10:13]
	v_mfma_f32_16x16x32_bf16 v[6:9], v[170:173], v[210:213], v[6:9]
	v_mfma_f32_16x16x32_bf16 v[2:5], v[178:181], v[210:213], v[2:5]
	s_nop 0
	s_barrier
	s_add_i32 s50, 0, 0x18000
	s_add_i32 s51, 0, 0x1c000
	v_add_u32_e32 v158, s50, v152
	v_add_u32_e32 v164, s51, v152
	ds_read_b128 v[142:145], v158
	ds_read_b128 v[146:149], v158 offset:1024
	ds_read_b128 v[154:157], v158 offset:2048
	ds_read_b128 v[158:161], v158 offset:3072
	ds_read_b128 v[166:169], v164
	ds_read_b128 v[170:173], v164 offset:1024
	ds_read_b128 v[174:177], v164 offset:2048
	ds_read_b128 v[178:181], v164 offset:3072
	s_add_u32 s22, s22, 0x60000
	s_addc_u32 s23, s23, 0
	s_mov_b32 m0, s28
	v_lshl_add_u64 v[220:221], s[22:23], 0, v[130:131]
	ds_read_b128 v[182:185], v153 offset:32768
	ds_read_b128 v[186:189], v153 offset:33792
	ds_read_b128 v[190:193], v153 offset:34816
	ds_read_b128 v[194:197], v153 offset:35840
	ds_read_b128 v[198:201], v153 offset:36864
	ds_read_b128 v[202:205], v153 offset:37888
	ds_read_b128 v[206:209], v153 offset:38912
	ds_read_b128 v[210:213], v153 offset:39936
	global_load_lds_dwordx4 v[220:221], off
	v_lshl_add_u64 v[220:221], s[22:23], 0, v[134:135]
	s_mov_b32 m0, s29
	s_nop 0
	global_load_lds_dwordx4 v[220:221], off
	s_waitcnt vmcnt(8)
	s_waitcnt lgkmcnt(0)
	s_barrier
	s_nop 0
	s_waitcnt lgkmcnt(0)
	v_mfma_f32_16x16x32_bf16 v[126:129], v[142:145], v[182:185], v[126:129]
	v_mfma_f32_16x16x32_bf16 v[122:125], v[154:157], v[182:185], v[122:125]
	v_mfma_f32_16x16x32_bf16 v[118:121], v[142:145], v[190:193], v[118:121]
	v_mfma_f32_16x16x32_bf16 v[114:117], v[154:157], v[190:193], v[114:117]
	v_mfma_f32_16x16x32_bf16 v[110:113], v[142:145], v[198:201], v[110:113]
	v_mfma_f32_16x16x32_bf16 v[106:109], v[154:157], v[198:201], v[106:109]
	v_mfma_f32_16x16x32_bf16 v[102:105], v[142:145], v[206:209], v[102:105]
	v_mfma_f32_16x16x32_bf16 v[98:101], v[154:157], v[206:209], v[98:101]
	v_mfma_f32_16x16x32_bf16 v[126:129], v[146:149], v[186:189], v[126:129]
	v_mfma_f32_16x16x32_bf16 v[122:125], v[158:161], v[186:189], v[122:125]
	v_mfma_f32_16x16x32_bf16 v[118:121], v[146:149], v[194:197], v[118:121]
	v_mfma_f32_16x16x32_bf16 v[114:117], v[158:161], v[194:197], v[114:117]
	v_mfma_f32_16x16x32_bf16 v[110:113], v[146:149], v[202:205], v[110:113]
	v_mfma_f32_16x16x32_bf16 v[106:109], v[158:161], v[202:205], v[106:109]
	v_mfma_f32_16x16x32_bf16 v[102:105], v[146:149], v[210:213], v[102:105]
	v_mfma_f32_16x16x32_bf16 v[98:101], v[158:161], v[210:213], v[98:101]
	s_nop 0
	s_nop 0
	v_mfma_f32_16x16x32_bf16 v[94:97], v[166:169], v[182:185], v[94:97]
	v_mfma_f32_16x16x32_bf16 v[90:93], v[174:177], v[182:185], v[90:93]
	v_mfma_f32_16x16x32_bf16 v[86:89], v[166:169], v[190:193], v[86:89]
	v_mfma_f32_16x16x32_bf16 v[82:85], v[174:177], v[190:193], v[82:85]
	v_mfma_f32_16x16x32_bf16 v[78:81], v[166:169], v[198:201], v[78:81]
	v_mfma_f32_16x16x32_bf16 v[74:77], v[174:177], v[198:201], v[74:77]
	v_mfma_f32_16x16x32_bf16 v[70:73], v[166:169], v[206:209], v[70:73]
	v_mfma_f32_16x16x32_bf16 v[66:69], v[174:177], v[206:209], v[66:69]
	v_mfma_f32_16x16x32_bf16 v[94:97], v[170:173], v[186:189], v[94:97]
	v_mfma_f32_16x16x32_bf16 v[90:93], v[178:181], v[186:189], v[90:93]
	v_mfma_f32_16x16x32_bf16 v[86:89], v[170:173], v[194:197], v[86:89]
	v_mfma_f32_16x16x32_bf16 v[82:85], v[178:181], v[194:197], v[82:85]
	v_mfma_f32_16x16x32_bf16 v[78:81], v[170:173], v[202:205], v[78:81]
	v_mfma_f32_16x16x32_bf16 v[74:77], v[178:181], v[202:205], v[74:77]
	v_mfma_f32_16x16x32_bf16 v[70:73], v[170:173], v[210:213], v[70:73]
	v_mfma_f32_16x16x32_bf16 v[66:69], v[178:181], v[210:213], v[66:69]
	s_nop 0
	s_barrier
	s_add_i32 s22, s50, s25
	v_lshl_add_u64 v[162:163], v[162:163], 0, s[8:9]
	s_mov_b32 m0, s22
	ds_read_b128 v[182:185], v153 offset:49152
	ds_read_b128 v[186:189], v153 offset:50176
	ds_read_b128 v[190:193], v153 offset:51200
	ds_read_b128 v[194:197], v153 offset:52224
	ds_read_b128 v[198:201], v153 offset:53248
	ds_read_b128 v[202:205], v153 offset:54272
	ds_read_b128 v[206:209], v153 offset:55296
	ds_read_b128 v[210:213], v153 offset:56320
	global_load_lds_dwordx4 v[162:163], off
	s_add_i32 m0, s22, 0x2000
	s_add_u32 s20, s20, 0x60080
	v_lshl_add_u64 v[162:163], v[214:215], 0, s[8:9]
	s_addc_u32 s21, s21, 0
	s_add_i32 s22, s51, s25
	global_load_lds_dwordx4 v[162:163], off
	v_lshl_add_u64 v[162:163], s[20:21], 0, v[132:133]
	s_mov_b32 m0, s22
	s_nop 0
	global_load_lds_dwordx4 v[162:163], off
	v_lshl_add_u64 v[162:163], s[20:21], 0, v[136:137]
	s_add_i32 m0, s22, 0x2000
	s_nop 0
	global_load_lds_dwordx4 v[162:163], off
	v_lshl_add_u64 v[162:163], v[216:217], 0, s[8:9]
	s_mov_b32 m0, s34
	s_nop 0
	global_load_lds_dwordx4 v[162:163], off
	v_lshl_add_u64 v[162:163], v[218:219], 0, s[8:9]
	s_mov_b32 m0, s35
	s_nop 0
	global_load_lds_dwordx4 v[162:163], off
	s_waitcnt vmcnt(8)
	s_waitcnt lgkmcnt(0)
	s_barrier
	s_nop 0
	s_waitcnt lgkmcnt(0)
	v_mfma_f32_16x16x32_bf16 v[62:65], v[142:145], v[182:185], v[62:65]
	v_mfma_f32_16x16x32_bf16 v[58:61], v[154:157], v[182:185], v[58:61]
	v_mfma_f32_16x16x32_bf16 v[54:57], v[142:145], v[190:193], v[54:57]
	v_mfma_f32_16x16x32_bf16 v[50:53], v[154:157], v[190:193], v[50:53]
	v_mfma_f32_16x16x32_bf16 v[46:49], v[142:145], v[198:201], v[46:49]
	v_mfma_f32_16x16x32_bf16 v[42:45], v[154:157], v[198:201], v[42:45]
	v_mfma_f32_16x16x32_bf16 v[38:41], v[142:145], v[206:209], v[38:41]
	v_mfma_f32_16x16x32_bf16 v[34:37], v[154:157], v[206:209], v[34:37]
	v_mfma_f32_16x16x32_bf16 v[62:65], v[146:149], v[186:189], v[62:65]
	v_mfma_f32_16x16x32_bf16 v[58:61], v[158:161], v[186:189], v[58:61]
	v_mfma_f32_16x16x32_bf16 v[54:57], v[146:149], v[194:197], v[54:57]
	v_mfma_f32_16x16x32_bf16 v[50:53], v[158:161], v[194:197], v[50:53]
	v_mfma_f32_16x16x32_bf16 v[46:49], v[146:149], v[202:205], v[46:49]
	v_mfma_f32_16x16x32_bf16 v[42:45], v[158:161], v[202:205], v[42:45]
	v_mfma_f32_16x16x32_bf16 v[38:41], v[146:149], v[210:213], v[38:41]
	v_mfma_f32_16x16x32_bf16 v[34:37], v[158:161], v[210:213], v[34:37]
	s_nop 0
	s_nop 0
	v_mfma_f32_16x16x32_bf16 v[30:33], v[166:169], v[182:185], v[30:33]
	v_mfma_f32_16x16x32_bf16 v[26:29], v[174:177], v[182:185], v[26:29]
	v_mfma_f32_16x16x32_bf16 v[22:25], v[166:169], v[190:193], v[22:25]
	v_mfma_f32_16x16x32_bf16 v[18:21], v[174:177], v[190:193], v[18:21]
	v_mfma_f32_16x16x32_bf16 v[14:17], v[166:169], v[198:201], v[14:17]
	v_mfma_f32_16x16x32_bf16 v[10:13], v[174:177], v[198:201], v[10:13]
	v_mfma_f32_16x16x32_bf16 v[6:9], v[166:169], v[206:209], v[6:9]
	v_mfma_f32_16x16x32_bf16 v[2:5], v[174:177], v[206:209], v[2:5]
	v_mfma_f32_16x16x32_bf16 v[30:33], v[170:173], v[186:189], v[30:33]
	v_mfma_f32_16x16x32_bf16 v[26:29], v[178:181], v[186:189], v[26:29]
	v_mfma_f32_16x16x32_bf16 v[22:25], v[170:173], v[194:197], v[22:25]
	v_mfma_f32_16x16x32_bf16 v[18:21], v[178:181], v[194:197], v[18:21]
	v_mfma_f32_16x16x32_bf16 v[14:17], v[170:173], v[202:205], v[14:17]
	v_mfma_f32_16x16x32_bf16 v[10:13], v[178:181], v[202:205], v[10:13]
	v_mfma_f32_16x16x32_bf16 v[6:9], v[170:173], v[210:213], v[6:9]
	v_mfma_f32_16x16x32_bf16 v[2:5], v[178:181], v[210:213], v[2:5]
	s_nop 0
	s_barrier
	s_add_u32 s4, s4, 0x100
	s_addc_u32 s5, s5, 0
	s_add_u32 s47, s47, 0x100
	s_addc_u32 s48, s48, 0
	s_cmp_ge_i32 s49, s45
	s_mov_b32 s20, s49
	s_cbranch_scc0 .LBB0_842
	s_setprio 0
	s_and_b64 vcc, exec, s[10:11]
	s_cbranch_vccz .LBB0_845
	s_barrier

.LBB0_1018:
	s_and_b64 s[30:31], s[22:23], exec
	s_cselect_b32 s1, s19, s27
	s_cselect_b32 s15, s18, s26
	s_cselect_b32 s17, s21, s29
	s_cselect_b32 s46, s20, s28
	s_add_u32 s26, s26, 0x80080
	s_addc_u32 s27, s27, 0
	s_add_u32 s47, s28, 0x100
	v_mov_b32_e32 v2, 0
	s_addc_u32 s48, s29, 0
	s_mov_b32 s49, -2
	s_waitcnt lgkmcnt(0)
	v_mov_b32_e32 v3, v2
	v_mov_b32_e32 v4, v2
	v_mov_b32_e32 v5, v2
	v_mov_b32_e32 v6, v2
	v_mov_b32_e32 v7, v2
	v_mov_b32_e32 v8, v2
	v_mov_b32_e32 v9, v2
	v_mov_b32_e32 v18, v2
	v_mov_b32_e32 v19, v2
	v_mov_b32_e32 v20, v2
	v_mov_b32_e32 v21, v2
	v_mov_b32_e32 v22, v2
	v_mov_b32_e32 v23, v2
	v_mov_b32_e32 v24, v2
	v_mov_b32_e32 v25, v2
	v_mov_b32_e32 v34, v2
	v_mov_b32_e32 v35, v2
	v_mov_b32_e32 v36, v2
	v_mov_b32_e32 v37, v2
	v_mov_b32_e32 v38, v2
	v_mov_b32_e32 v39, v2
	v_mov_b32_e32 v40, v2
	v_mov_b32_e32 v41, v2
	v_mov_b32_e32 v50, v2
	v_mov_b32_e32 v51, v2
	v_mov_b32_e32 v52, v2
	v_mov_b32_e32 v53, v2
	v_mov_b32_e32 v54, v2
	v_mov_b32_e32 v55, v2
	v_mov_b32_e32 v56, v2
	v_mov_b32_e32 v57, v2
	v_mov_b32_e32 v10, v2
	v_mov_b32_e32 v11, v2
	v_mov_b32_e32 v12, v2
	v_mov_b32_e32 v13, v2
	v_mov_b32_e32 v14, v2
	v_mov_b32_e32 v15, v2
	v_mov_b32_e32 v16, v2
	v_mov_b32_e32 v17, v2
	v_mov_b32_e32 v26, v2
	v_mov_b32_e32 v27, v2
	v_mov_b32_e32 v28, v2
	v_mov_b32_e32 v29, v2
	v_mov_b32_e32 v30, v2
	v_mov_b32_e32 v31, v2
	v_mov_b32_e32 v32, v2
	v_mov_b32_e32 v33, v2
	v_mov_b32_e32 v42, v2
	v_mov_b32_e32 v43, v2
	v_mov_b32_e32 v44, v2
	v_mov_b32_e32 v45, v2
	v_mov_b32_e32 v46, v2
	v_mov_b32_e32 v47, v2
	v_mov_b32_e32 v48, v2
	v_mov_b32_e32 v49, v2
	v_mov_b32_e32 v58, v2
	v_mov_b32_e32 v59, v2
	v_mov_b32_e32 v60, v2
	v_mov_b32_e32 v61, v2
	v_mov_b32_e32 v62, v2
	v_mov_b32_e32 v63, v2
	v_mov_b32_e32 v64, v2
	v_mov_b32_e32 v65, v2
	v_mov_b32_e32 v66, v2
	v_mov_b32_e32 v67, v2
	v_mov_b32_e32 v68, v2
	v_mov_b32_e32 v69, v2
	v_mov_b32_e32 v70, v2
	v_mov_b32_e32 v71, v2
	v_mov_b32_e32 v72, v2
	v_mov_b32_e32 v73, v2
	v_mov_b32_e32 v82, v2
	v_mov_b32_e32 v83, v2
	v_mov_b32_e32 v84, v2
	v_mov_b32_e32 v85, v2
	v_mov_b32_e32 v86, v2
	v_mov_b32_e32 v87, v2
	v_mov_b32_e32 v88, v2
	v_mov_b32_e32 v89, v2
	v_mov_b32_e32 v98, v2
	v_mov_b32_e32 v99, v2
	v_mov_b32_e32 v100, v2
	v_mov_b32_e32 v101, v2
	v_mov_b32_e32 v102, v2
	v_mov_b32_e32 v103, v2
	v_mov_b32_e32 v104, v2
	v_mov_b32_e32 v105, v2
	v_mov_b32_e32 v114, v2
	v_mov_b32_e32 v115, v2
	v_mov_b32_e32 v116, v2
	v_mov_b32_e32 v117, v2
	v_mov_b32_e32 v118, v2
	v_mov_b32_e32 v119, v2
	v_mov_b32_e32 v120, v2
	v_mov_b32_e32 v121, v2
	v_mov_b32_e32 v74, v2
	v_mov_b32_e32 v75, v2
	v_mov_b32_e32 v76, v2
	v_mov_b32_e32 v77, v2
	v_mov_b32_e32 v78, v2
	v_mov_b32_e32 v79, v2
	v_mov_b32_e32 v80, v2
	v_mov_b32_e32 v81, v2
	v_mov_b32_e32 v90, v2
	v_mov_b32_e32 v91, v2
	v_mov_b32_e32 v92, v2
	v_mov_b32_e32 v93, v2
	v_mov_b32_e32 v94, v2
	v_mov_b32_e32 v95, v2
	v_mov_b32_e32 v96, v2
	v_mov_b32_e32 v97, v2
	v_mov_b32_e32 v106, v2
	v_mov_b32_e32 v107, v2
	v_mov_b32_e32 v108, v2
	v_mov_b32_e32 v109, v2
	v_mov_b32_e32 v110, v2
	v_mov_b32_e32 v111, v2
	v_mov_b32_e32 v112, v2
	v_mov_b32_e32 v113, v2
	v_mov_b32_e32 v122, v2
	v_mov_b32_e32 v123, v2
	v_mov_b32_e32 v124, v2
	v_mov_b32_e32 v125, v2
	v_mov_b32_e32 v126, v2
	v_mov_b32_e32 v127, v2
	v_mov_b32_e32 v128, v2
	v_mov_b32_e32 v129, v2
	s_and_b64 s[98:99], exec, s[10:11]
	s_cbranch_scc1 .Lsp_p6
	s_setprio 1
.Lsp_p6:
.LBB0_1019:
	ds_read_b128 v[142:145], v149
	ds_read_b128 v[154:157], v149 offset:1024
	ds_read_b128 v[158:161], v149 offset:2048
	ds_read_b128 v[166:169], v149 offset:3072
	ds_read_b128 v[170:173], v150
	ds_read_b128 v[174:177], v150 offset:1024
	ds_read_b128 v[178:181], v150 offset:2048
	ds_read_b128 v[182:185], v150 offset:3072
	s_add_u32 s28, s26, 0xfff80080
	s_addc_u32 s29, s27, -1
	s_cmp_eq_u32 s49, 28
	s_cselect_b32 s31, s1, s29
	s_cselect_b32 s30, s15, s28
	s_cselect_b32 s29, s17, s48
	s_cselect_b32 s28, s46, s47
	v_lshl_add_u64 v[162:163], s[26:27], 0, v[138:139]
	s_add_i32 m0, s34, 0xc000
	ds_read_b128 v[186:189], v151
	ds_read_b128 v[190:193], v151 offset:1024
	ds_read_b128 v[194:197], v151 offset:2048
	ds_read_b128 v[198:201], v151 offset:3072
	ds_read_b128 v[202:205], v151 offset:4096
	ds_read_b128 v[206:209], v151 offset:5120
	ds_read_b128 v[210:213], v151 offset:6144
	ds_read_b128 v[214:217], v151 offset:7168
	global_load_lds_dwordx4 v[162:163], off
	v_lshl_add_u64 v[162:163], s[26:27], 0, v[140:141]
	s_add_i32 m0, s34, 0xe000
	s_nop 0
	global_load_lds_dwordx4 v[162:163], off
	s_waitcnt vmcnt(8)
	s_waitcnt lgkmcnt(0)
	s_barrier
	s_nop 0
	s_waitcnt lgkmcnt(0)
	v_mfma_f32_16x16x32_bf16 v[126:129], v[142:145], v[186:189], v[126:129]
	v_mfma_f32_16x16x32_bf16 v[122:125], v[158:161], v[186:189], v[122:125]
	v_mfma_f32_16x16x32_bf16 v[110:113], v[142:145], v[194:197], v[110:113]
	v_mfma_f32_16x16x32_bf16 v[106:109], v[158:161], v[194:197], v[106:109]
	v_mfma_f32_16x16x32_bf16 v[94:97], v[142:145], v[202:205], v[94:97]
	v_mfma_f32_16x16x32_bf16 v[90:93], v[158:161], v[202:205], v[90:93]
	v_mfma_f32_16x16x32_bf16 v[78:81], v[142:145], v[210:213], v[78:81]
	v_mfma_f32_16x16x32_bf16 v[74:77], v[158:161], v[210:213], v[74:77]
	v_mfma_f32_16x16x32_bf16 v[126:129], v[154:157], v[190:193], v[126:129]
	v_mfma_f32_16x16x32_bf16 v[122:125], v[166:169], v[190:193], v[122:125]
	v_mfma_f32_16x16x32_bf16 v[110:113], v[154:157], v[198:201], v[110:113]
	v_mfma_f32_16x16x32_bf16 v[106:109], v[166:169], v[198:201], v[106:109]
	v_mfma_f32_16x16x32_bf16 v[94:97], v[154:157], v[206:209], v[94:97]
	v_mfma_f32_16x16x32_bf16 v[90:93], v[166:169], v[206:209], v[90:93]
	v_mfma_f32_16x16x32_bf16 v[78:81], v[154:157], v[214:217], v[78:81]
	v_mfma_f32_16x16x32_bf16 v[74:77], v[166:169], v[214:217], v[74:77]
	s_nop 0
	s_nop 0
	v_mfma_f32_16x16x32_bf16 v[118:121], v[170:173], v[186:189], v[118:121]
	v_mfma_f32_16x16x32_bf16 v[114:117], v[178:181], v[186:189], v[114:117]
	v_mfma_f32_16x16x32_bf16 v[102:105], v[170:173], v[194:197], v[102:105]
	v_mfma_f32_16x16x32_bf16 v[98:101], v[178:181], v[194:197], v[98:101]
	v_mfma_f32_16x16x32_bf16 v[86:89], v[170:173], v[202:205], v[86:89]
	v_mfma_f32_16x16x32_bf16 v[82:85], v[178:181], v[202:205], v[82:85]
	v_mfma_f32_16x16x32_bf16 v[70:73], v[170:173], v[210:213], v[70:73]
	v_mfma_f32_16x16x32_bf16 v[66:69], v[178:181], v[210:213], v[66:69]
	v_mfma_f32_16x16x32_bf16 v[118:121], v[174:177], v[190:193], v[118:121]
	v_mfma_f32_16x16x32_bf16 v[114:117], v[182:185], v[190:193], v[114:117]
	v_mfma_f32_16x16x32_bf16 v[102:105], v[174:177], v[198:201], v[102:105]
	v_mfma_f32_16x16x32_bf16 v[98:101], v[182:185], v[198:201], v[98:101]
	v_mfma_f32_16x16x32_bf16 v[86:89], v[174:177], v[206:209], v[86:89]
	v_mfma_f32_16x16x32_bf16 v[82:85], v[182:185], v[206:209], v[82:85]
	v_mfma_f32_16x16x32_bf16 v[70:73], v[174:177], v[214:217], v[70:73]
	v_mfma_f32_16x16x32_bf16 v[66:69], v[182:185], v[214:217], v[66:69]
	s_nop 0
	s_barrier
	s_add_i32 s50, s44, s25
	v_lshl_add_u64 v[162:163], s[28:29], 0, v[132:133]
	s_mov_b32 m0, s50
	ds_read_b128 v[186:189], v151 offset:16384
	ds_read_b128 v[190:193], v151 offset:17408
	ds_read_b128 v[194:197], v151 offset:18432
	ds_read_b128 v[198:201], v151 offset:19456
	ds_read_b128 v[202:205], v151 offset:20480
	ds_read_b128 v[206:209], v151 offset:21504
	ds_read_b128 v[210:213], v151 offset:22528
	ds_read_b128 v[214:217], v151 offset:23552
	global_load_lds_dwordx4 v[162:163], off
	s_add_i32 m0, s50, 0x2000
	s_add_u32 s50, s28, 0x80000
	v_lshl_add_u64 v[218:219], s[28:29], 0, v[136:137]
	s_addc_u32 s51, s29, 0
	s_add_i32 s52, s45, s25
	global_load_lds_dwordx4 v[218:219], off
	v_lshl_add_u64 v[220:221], s[50:51], 0, v[132:133]
	s_mov_b32 m0, s52
	v_lshl_add_u64 v[222:223], s[30:31], 0, v[134:135]
	global_load_lds_dwordx4 v[220:221], off
	v_lshl_add_u64 v[220:221], s[50:51], 0, v[136:137]
	s_add_i32 m0, s52, 0x2000
	s_nop 0
	global_load_lds_dwordx4 v[220:221], off
	v_lshl_add_u64 v[220:221], s[30:31], 0, v[130:131]
	s_mov_b32 m0, s34
	s_nop 0
	global_load_lds_dwordx4 v[220:221], off
	s_mov_b32 m0, s35
	s_nop 0
	global_load_lds_dwordx4 v[222:223], off
	s_waitcnt vmcnt(8)
	s_waitcnt lgkmcnt(0)
	s_barrier
	s_nop 0
	s_waitcnt lgkmcnt(0)
	v_mfma_f32_16x16x32_bf16 v[62:65], v[142:145], v[186:189], v[62:65]
	v_mfma_f32_16x16x32_bf16 v[58:61], v[158:161], v[186:189], v[58:61]
	v_mfma_f32_16x16x32_bf16 v[46:49], v[142:145], v[194:197], v[46:49]
	v_mfma_f32_16x16x32_bf16 v[42:45], v[158:161], v[194:197], v[42:45]
	v_mfma_f32_16x16x32_bf16 v[30:33], v[142:145], v[202:205], v[30:33]
	v_mfma_f32_16x16x32_bf16 v[26:29], v[158:161], v[202:205], v[26:29]
	v_mfma_f32_16x16x32_bf16 v[14:17], v[142:145], v[210:213], v[14:17]
	v_mfma_f32_16x16x32_bf16 v[10:13], v[158:161], v[210:213], v[10:13]
	v_mfma_f32_16x16x32_bf16 v[62:65], v[154:157], v[190:193], v[62:65]
	v_mfma_f32_16x16x32_bf16 v[58:61], v[166:169], v[190:193], v[58:61]
	v_mfma_f32_16x16x32_bf16 v[46:49], v[154:157], v[198:201], v[46:49]
	v_mfma_f32_16x16x32_bf16 v[42:45], v[166:169], v[198:201], v[42:45]
	v_mfma_f32_16x16x32_bf16 v[30:33], v[154:157], v[206:209], v[30:33]
	v_mfma_f32_16x16x32_bf16 v[26:29], v[166:169], v[206:209], v[26:29]
	v_mfma_f32_16x16x32_bf16 v[14:17], v[154:157], v[214:217], v[14:17]
	v_mfma_f32_16x16x32_bf16 v[10:13], v[166:169], v[214:217], v[10:13]
	s_nop 0
	s_nop 0
	v_mfma_f32_16x16x32_bf16 v[54:57], v[170:173], v[186:189], v[54:57]
	v_mfma_f32_16x16x32_bf16 v[50:53], v[178:181], v[186:189], v[50:53]
	v_mfma_f32_16x16x32_bf16 v[38:41], v[170:173], v[194:197], v[38:41]
	v_mfma_f32_16x16x32_bf16 v[34:37], v[178:181], v[194:197], v[34:37]
	v_mfma_f32_16x16x32_bf16 v[22:25], v[170:173], v[202:205], v[22:25]
	v_mfma_f32_16x16x32_bf16 v[18:21], v[178:181], v[202:205], v[18:21]
	v_mfma_f32_16x16x32_bf16 v[6:9], v[170:173], v[210:213], v[6:9]
	v_mfma_f32_16x16x32_bf16 v[2:5], v[178:181], v[210:213], v[2:5]
	v_mfma_f32_16x16x32_bf16 v[54:57], v[174:177], v[190:193], v[54:57]
	v_mfma_f32_16x16x32_bf16 v[50:53], v[182:185], v[190:193], v[50:53]
	v_mfma_f32_16x16x32_bf16 v[38:41], v[174:177], v[198:201], v[38:41]
	v_mfma_f32_16x16x32_bf16 v[34:37], v[182:185], v[198:201], v[34:37]
	v_mfma_f32_16x16x32_bf16 v[22:25], v[174:177], v[206:209], v[22:25]
	v_mfma_f32_16x16x32_bf16 v[18:21], v[182:185], v[206:209], v[18:21]
	v_mfma_f32_16x16x32_bf16 v[6:9], v[174:177], v[214:217], v[6:9]
	v_mfma_f32_16x16x32_bf16 v[2:5], v[182:185], v[214:217], v[2:5]
	s_nop 0
	s_barrier
	s_add_i32 s50, 0, 0x18000
	v_add_u32_e32 v153, s50, v148
	s_add_i32 s51, 0, 0x1c000
	ds_read_b128 v[142:145], v153
	ds_read_b128 v[154:157], v153 offset:1024
	ds_read_b128 v[158:161], v153 offset:2048
	ds_read_b128 v[166:169], v153 offset:3072
	v_add_u32_e32 v153, s51, v148
	ds_read_b128 v[170:173], v153
	ds_read_b128 v[174:177], v153 offset:1024
	ds_read_b128 v[178:181], v153 offset:2048
	ds_read_b128 v[182:185], v153 offset:3072
	s_add_u32 s30, s30, 0x80000
	s_addc_u32 s31, s31, 0
	s_mov_b32 m0, s36
	v_lshl_add_u64 v[224:225], s[30:31], 0, v[130:131]
	ds_read_b128 v[186:189], v151 offset:32768
	ds_read_b128 v[190:193], v151 offset:33792
	ds_read_b128 v[194:197], v151 offset:34816
	ds_read_b128 v[198:201], v151 offset:35840
	ds_read_b128 v[202:205], v151 offset:36864
	ds_read_b128 v[206:209], v151 offset:37888
	ds_read_b128 v[210:213], v151 offset:38912
	ds_read_b128 v[214:217], v151 offset:39936
	global_load_lds_dwordx4 v[224:225], off
	v_lshl_add_u64 v[224:225], s[30:31], 0, v[134:135]
	s_mov_b32 m0, s37
	s_nop 0
	global_load_lds_dwordx4 v[224:225], off
	s_waitcnt vmcnt(8)
	s_waitcnt lgkmcnt(0)
	s_barrier
	s_nop 0
	s_waitcnt lgkmcnt(0)
	v_mfma_f32_16x16x32_bf16 v[126:129], v[142:145], v[186:189], v[126:129]
	v_mfma_f32_16x16x32_bf16 v[122:125], v[158:161], v[186:189], v[122:125]
	v_mfma_f32_16x16x32_bf16 v[110:113], v[142:145], v[194:197], v[110:113]
	v_mfma_f32_16x16x32_bf16 v[106:109], v[158:161], v[194:197], v[106:109]
	v_mfma_f32_16x16x32_bf16 v[94:97], v[142:145], v[202:205], v[94:97]
	v_mfma_f32_16x16x32_bf16 v[90:93], v[158:161], v[202:205], v[90:93]
	v_mfma_f32_16x16x32_bf16 v[78:81], v[142:145], v[210:213], v[78:81]
	v_mfma_f32_16x16x32_bf16 v[74:77], v[158:161], v[210:213], v[74:77]
	v_mfma_f32_16x16x32_bf16 v[126:129], v[154:157], v[190:193], v[126:129]
	v_mfma_f32_16x16x32_bf16 v[122:125], v[166:169], v[190:193], v[122:125]
	v_mfma_f32_16x16x32_bf16 v[110:113], v[154:157], v[198:201], v[110:113]
	v_mfma_f32_16x16x32_bf16 v[106:109], v[166:169], v[198:201], v[106:109]
	v_mfma_f32_16x16x32_bf16 v[94:97], v[154:157], v[206:209], v[94:97]
	v_mfma_f32_16x16x32_bf16 v[90:93], v[166:169], v[206:209], v[90:93]
	v_mfma_f32_16x16x32_bf16 v[78:81], v[154:157], v[214:217], v[78:81]
	v_mfma_f32_16x16x32_bf16 v[74:77], v[166:169], v[214:217], v[74:77]
	s_nop 0
	s_nop 0
	v_mfma_f32_16x16x32_bf16 v[118:121], v[170:173], v[186:189], v[118:121]
	v_mfma_f32_16x16x32_bf16 v[114:117], v[178:181], v[186:189], v[114:117]
	v_mfma_f32_16x16x32_bf16 v[102:105], v[170:173], v[194:197], v[102:105]
	v_mfma_f32_16x16x32_bf16 v[98:101], v[178:181], v[194:197], v[98:101]
	v_mfma_f32_16x16x32_bf16 v[86:89], v[170:173], v[202:205], v[86:89]
	v_mfma_f32_16x16x32_bf16 v[82:85], v[178:181], v[202:205], v[82:85]
	v_mfma_f32_16x16x32_bf16 v[70:73], v[170:173], v[210:213], v[70:73]
	v_mfma_f32_16x16x32_bf16 v[66:69], v[178:181], v[210:213], v[66:69]
	v_mfma_f32_16x16x32_bf16 v[118:121], v[174:177], v[190:193], v[118:121]
	v_mfma_f32_16x16x32_bf16 v[114:117], v[182:185], v[190:193], v[114:117]
	v_mfma_f32_16x16x32_bf16 v[102:105], v[174:177], v[198:201], v[102:105]
	v_mfma_f32_16x16x32_bf16 v[98:101], v[182:185], v[198:201], v[98:101]
	v_mfma_f32_16x16x32_bf16 v[86:89], v[174:177], v[206:209], v[86:89]
	v_mfma_f32_16x16x32_bf16 v[82:85], v[182:185], v[206:209], v[82:85]
	v_mfma_f32_16x16x32_bf16 v[70:73], v[174:177], v[214:217], v[70:73]
	v_mfma_f32_16x16x32_bf16 v[66:69], v[182:185], v[214:217], v[66:69]
	s_nop 0
	s_barrier
	s_add_i32 s30, s50, s25
	v_lshl_add_u64 v[162:163], v[162:163], 0, s[8:9]
	s_mov_b32 m0, s30
	ds_read_b128 v[186:189], v151 offset:49152
	ds_read_b128 v[190:193], v151 offset:50176
	ds_read_b128 v[194:197], v151 offset:51200
	ds_read_b128 v[198:201], v151 offset:52224
	ds_read_b128 v[202:205], v151 offset:53248
	ds_read_b128 v[206:209], v151 offset:54272
	ds_read_b128 v[210:213], v151 offset:55296
	ds_read_b128 v[214:217], v151 offset:56320
	global_load_lds_dwordx4 v[162:163], off
	s_add_i32 m0, s30, 0x2000
	s_add_u32 s28, s28, 0x80080
	v_lshl_add_u64 v[162:163], v[218:219], 0, s[8:9]
	s_addc_u32 s29, s29, 0
	s_add_i32 s30, s51, s25
	global_load_lds_dwordx4 v[162:163], off
	v_lshl_add_u64 v[162:163], s[28:29], 0, v[132:133]
	s_mov_b32 m0, s30
	s_nop 0
	global_load_lds_dwordx4 v[162:163], off
	v_lshl_add_u64 v[162:163], s[28:29], 0, v[136:137]
	s_add_i32 m0, s30, 0x2000
	s_nop 0
	global_load_lds_dwordx4 v[162:163], off
	v_lshl_add_u64 v[162:163], v[220:221], 0, s[8:9]
	s_mov_b32 m0, s41
	s_nop 0
	global_load_lds_dwordx4 v[162:163], off
	v_lshl_add_u64 v[162:163], v[222:223], 0, s[8:9]
	s_mov_b32 m0, s42
	s_nop 0
	global_load_lds_dwordx4 v[162:163], off
	s_waitcnt vmcnt(8)
	s_waitcnt lgkmcnt(0)
	s_barrier
	s_nop 0
	s_waitcnt lgkmcnt(0)
	v_mfma_f32_16x16x32_bf16 v[62:65], v[142:145], v[186:189], v[62:65]
	v_mfma_f32_16x16x32_bf16 v[58:61], v[158:161], v[186:189], v[58:61]
	v_mfma_f32_16x16x32_bf16 v[46:49], v[142:145], v[194:197], v[46:49]
	v_mfma_f32_16x16x32_bf16 v[42:45], v[158:161], v[194:197], v[42:45]
	v_mfma_f32_16x16x32_bf16 v[30:33], v[142:145], v[202:205], v[30:33]
	v_mfma_f32_16x16x32_bf16 v[26:29], v[158:161], v[202:205], v[26:29]
	v_mfma_f32_16x16x32_bf16 v[14:17], v[142:145], v[210:213], v[14:17]
	v_mfma_f32_16x16x32_bf16 v[10:13], v[158:161], v[210:213], v[10:13]
	v_mfma_f32_16x16x32_bf16 v[62:65], v[154:157], v[190:193], v[62:65]
	v_mfma_f32_16x16x32_bf16 v[58:61], v[166:169], v[190:193], v[58:61]
	v_mfma_f32_16x16x32_bf16 v[46:49], v[154:157], v[198:201], v[46:49]
	v_mfma_f32_16x16x32_bf16 v[42:45], v[166:169], v[198:201], v[42:45]
	v_mfma_f32_16x16x32_bf16 v[30:33], v[154:157], v[206:209], v[30:33]
	v_mfma_f32_16x16x32_bf16 v[26:29], v[166:169], v[206:209], v[26:29]
	v_mfma_f32_16x16x32_bf16 v[14:17], v[154:157], v[214:217], v[14:17]
	v_mfma_f32_16x16x32_bf16 v[10:13], v[166:169], v[214:217], v[10:13]
	s_nop 0
	s_nop 0
	v_mfma_f32_16x16x32_bf16 v[54:57], v[170:173], v[186:189], v[54:57]
	v_mfma_f32_16x16x32_bf16 v[50:53], v[178:181], v[186:189], v[50:53]
	v_mfma_f32_16x16x32_bf16 v[38:41], v[170:173], v[194:197], v[38:41]
	v_mfma_f32_16x16x32_bf16 v[34:37], v[178:181], v[194:197], v[34:37]
	v_mfma_f32_16x16x32_bf16 v[22:25], v[170:173], v[202:205], v[22:25]
	v_mfma_f32_16x16x32_bf16 v[18:21], v[178:181], v[202:205], v[18:21]
	v_mfma_f32_16x16x32_bf16 v[6:9], v[170:173], v[210:213], v[6:9]
	v_mfma_f32_16x16x32_bf16 v[2:5], v[178:181], v[210:213], v[2:5]
	v_mfma_f32_16x16x32_bf16 v[54:57], v[174:177], v[190:193], v[54:57]
	v_mfma_f32_16x16x32_bf16 v[50:53], v[182:185], v[190:193], v[50:53]
	v_mfma_f32_16x16x32_bf16 v[38:41], v[174:177], v[198:201], v[38:41]
	v_mfma_f32_16x16x32_bf16 v[34:37], v[182:185], v[198:201], v[34:37]
	v_mfma_f32_16x16x32_bf16 v[22:25], v[174:177], v[206:209], v[22:25]
	v_mfma_f32_16x16x32_bf16 v[18:21], v[182:185], v[206:209], v[18:21]
	v_mfma_f32_16x16x32_bf16 v[6:9], v[174:177], v[214:217], v[6:9]
	v_mfma_f32_16x16x32_bf16 v[2:5], v[182:185], v[214:217], v[2:5]
	s_nop 0
	s_barrier
	s_add_i32 s49, s49, 2
	s_add_u32 s26, s26, 0x100
	s_addc_u32 s27, s27, 0
	s_add_u32 s47, s47, 0x100
	s_addc_u32 s48, s48, 0
	s_cmp_gt_u32 s49, 29
	s_cbranch_scc0 .LBB0_1019
	s_setprio 0
	s_and_b64 vcc, exec, s[10:11]
	s_cbranch_vccz .LBB0_1022
	s_barrier

.LBB0_1219:
	s_and_b64 s[34:35], s[24:25], exec
	s_cselect_b32 s1, s21, s29
	s_cselect_b32 s17, s20, s28
	s_cselect_b32 s19, s23, s31
	s_cselect_b32 s48, s22, s30
	s_add_u32 s28, s28, 0x20080
	s_addc_u32 s29, s29, 0
	s_add_u32 s49, s30, 0x100
	v_mov_b32_e32 v2, 0
	s_addc_u32 s50, s31, 0
	s_mov_b32 s51, -2
	s_waitcnt lgkmcnt(0)
	v_mov_b32_e32 v3, v2
	v_mov_b32_e32 v4, v2
	v_mov_b32_e32 v5, v2
	v_mov_b32_e32 v6, v2
	v_mov_b32_e32 v7, v2
	v_mov_b32_e32 v8, v2
	v_mov_b32_e32 v9, v2
	v_mov_b32_e32 v18, v2
	v_mov_b32_e32 v19, v2
	v_mov_b32_e32 v20, v2
	v_mov_b32_e32 v21, v2
	v_mov_b32_e32 v22, v2
	v_mov_b32_e32 v23, v2
	v_mov_b32_e32 v24, v2
	v_mov_b32_e32 v25, v2
	v_mov_b32_e32 v34, v2
	v_mov_b32_e32 v35, v2
	v_mov_b32_e32 v36, v2
	v_mov_b32_e32 v37, v2
	v_mov_b32_e32 v38, v2
	v_mov_b32_e32 v39, v2
	v_mov_b32_e32 v40, v2
	v_mov_b32_e32 v41, v2
	v_mov_b32_e32 v50, v2
	v_mov_b32_e32 v51, v2
	v_mov_b32_e32 v52, v2
	v_mov_b32_e32 v53, v2
	v_mov_b32_e32 v54, v2
	v_mov_b32_e32 v55, v2
	v_mov_b32_e32 v56, v2
	v_mov_b32_e32 v57, v2
	v_mov_b32_e32 v10, v2
	v_mov_b32_e32 v11, v2
	v_mov_b32_e32 v12, v2
	v_mov_b32_e32 v13, v2
	v_mov_b32_e32 v14, v2
	v_mov_b32_e32 v15, v2
	v_mov_b32_e32 v16, v2
	v_mov_b32_e32 v17, v2
	v_mov_b32_e32 v26, v2
	v_mov_b32_e32 v27, v2
	v_mov_b32_e32 v28, v2
	v_mov_b32_e32 v29, v2
	v_mov_b32_e32 v30, v2
	v_mov_b32_e32 v31, v2
	v_mov_b32_e32 v32, v2
	v_mov_b32_e32 v33, v2
	v_mov_b32_e32 v42, v2
	v_mov_b32_e32 v43, v2
	v_mov_b32_e32 v44, v2
	v_mov_b32_e32 v45, v2
	v_mov_b32_e32 v46, v2
	v_mov_b32_e32 v47, v2
	v_mov_b32_e32 v48, v2
	v_mov_b32_e32 v49, v2
	v_mov_b32_e32 v58, v2
	v_mov_b32_e32 v59, v2
	v_mov_b32_e32 v60, v2
	v_mov_b32_e32 v61, v2
	v_mov_b32_e32 v62, v2
	v_mov_b32_e32 v63, v2
	v_mov_b32_e32 v64, v2
	v_mov_b32_e32 v65, v2
	v_mov_b32_e32 v66, v2
	v_mov_b32_e32 v67, v2
	v_mov_b32_e32 v68, v2
	v_mov_b32_e32 v69, v2
	v_mov_b32_e32 v70, v2
	v_mov_b32_e32 v71, v2
	v_mov_b32_e32 v72, v2
	v_mov_b32_e32 v73, v2
	v_mov_b32_e32 v82, v2
	v_mov_b32_e32 v83, v2
	v_mov_b32_e32 v84, v2
	v_mov_b32_e32 v85, v2
	v_mov_b32_e32 v86, v2
	v_mov_b32_e32 v87, v2
	v_mov_b32_e32 v88, v2
	v_mov_b32_e32 v89, v2
	v_mov_b32_e32 v98, v2
	v_mov_b32_e32 v99, v2
	v_mov_b32_e32 v100, v2
	v_mov_b32_e32 v101, v2
	v_mov_b32_e32 v102, v2
	v_mov_b32_e32 v103, v2
	v_mov_b32_e32 v104, v2
	v_mov_b32_e32 v105, v2
	v_mov_b32_e32 v114, v2
	v_mov_b32_e32 v115, v2
	v_mov_b32_e32 v116, v2
	v_mov_b32_e32 v117, v2
	v_mov_b32_e32 v118, v2
	v_mov_b32_e32 v119, v2
	v_mov_b32_e32 v120, v2
	v_mov_b32_e32 v121, v2
	v_mov_b32_e32 v74, v2
	v_mov_b32_e32 v75, v2
	v_mov_b32_e32 v76, v2
	v_mov_b32_e32 v77, v2
	v_mov_b32_e32 v78, v2
	v_mov_b32_e32 v79, v2
	v_mov_b32_e32 v80, v2
	v_mov_b32_e32 v81, v2
	v_mov_b32_e32 v90, v2
	v_mov_b32_e32 v91, v2
	v_mov_b32_e32 v92, v2
	v_mov_b32_e32 v93, v2
	v_mov_b32_e32 v94, v2
	v_mov_b32_e32 v95, v2
	v_mov_b32_e32 v96, v2
	v_mov_b32_e32 v97, v2
	v_mov_b32_e32 v106, v2
	v_mov_b32_e32 v107, v2
	v_mov_b32_e32 v108, v2
	v_mov_b32_e32 v109, v2
	v_mov_b32_e32 v110, v2
	v_mov_b32_e32 v111, v2
	v_mov_b32_e32 v112, v2
	v_mov_b32_e32 v113, v2
	v_mov_b32_e32 v122, v2
	v_mov_b32_e32 v123, v2
	v_mov_b32_e32 v124, v2
	v_mov_b32_e32 v125, v2
	v_mov_b32_e32 v126, v2
	v_mov_b32_e32 v127, v2
	v_mov_b32_e32 v128, v2
	v_mov_b32_e32 v129, v2
	s_and_b64 s[98:99], exec, s[12:13]
	s_cbranch_scc1 .Lsp_p9
	s_setprio 1
.Lsp_p9:
.LBB0_1220:
	ds_read_b128 v[142:145], v149
	ds_read_b128 v[154:157], v149 offset:1024
	ds_read_b128 v[158:161], v149 offset:2048
	ds_read_b128 v[166:169], v149 offset:3072
	ds_read_b128 v[170:173], v150
	ds_read_b128 v[174:177], v150 offset:1024
	ds_read_b128 v[178:181], v150 offset:2048
	ds_read_b128 v[182:185], v150 offset:3072
	s_add_u32 s30, s28, 0xfffe0080
	s_addc_u32 s31, s29, -1
	s_cmp_eq_u32 s51, 4
	s_cselect_b32 s35, s1, s31
	s_cselect_b32 s34, s17, s30
	s_cselect_b32 s31, s19, s50
	s_cselect_b32 s30, s48, s49
	v_lshl_add_u64 v[162:163], s[28:29], 0, v[138:139]
	s_add_i32 m0, s27, 0xc000
	ds_read_b128 v[186:189], v151
	ds_read_b128 v[190:193], v151 offset:1024
	ds_read_b128 v[194:197], v151 offset:2048
	ds_read_b128 v[198:201], v151 offset:3072
	ds_read_b128 v[202:205], v151 offset:4096
	ds_read_b128 v[206:209], v151 offset:5120
	ds_read_b128 v[210:213], v151 offset:6144
	ds_read_b128 v[214:217], v151 offset:7168
	global_load_lds_dwordx4 v[162:163], off
	v_lshl_add_u64 v[162:163], s[28:29], 0, v[140:141]
	s_add_i32 m0, s27, 0xe000
	s_nop 0
	global_load_lds_dwordx4 v[162:163], off
	s_waitcnt vmcnt(8)
	s_waitcnt lgkmcnt(0)
	s_barrier
	s_nop 0
	s_waitcnt lgkmcnt(0)
	v_mfma_f32_16x16x32_bf16 v[126:129], v[142:145], v[186:189], v[126:129]
	v_mfma_f32_16x16x32_bf16 v[122:125], v[158:161], v[186:189], v[122:125]
	v_mfma_f32_16x16x32_bf16 v[110:113], v[142:145], v[194:197], v[110:113]
	v_mfma_f32_16x16x32_bf16 v[106:109], v[158:161], v[194:197], v[106:109]
	v_mfma_f32_16x16x32_bf16 v[94:97], v[142:145], v[202:205], v[94:97]
	v_mfma_f32_16x16x32_bf16 v[90:93], v[158:161], v[202:205], v[90:93]
	v_mfma_f32_16x16x32_bf16 v[78:81], v[142:145], v[210:213], v[78:81]
	v_mfma_f32_16x16x32_bf16 v[74:77], v[158:161], v[210:213], v[74:77]
	v_mfma_f32_16x16x32_bf16 v[126:129], v[154:157], v[190:193], v[126:129]
	v_mfma_f32_16x16x32_bf16 v[122:125], v[166:169], v[190:193], v[122:125]
	v_mfma_f32_16x16x32_bf16 v[110:113], v[154:157], v[198:201], v[110:113]
	v_mfma_f32_16x16x32_bf16 v[106:109], v[166:169], v[198:201], v[106:109]
	v_mfma_f32_16x16x32_bf16 v[94:97], v[154:157], v[206:209], v[94:97]
	v_mfma_f32_16x16x32_bf16 v[90:93], v[166:169], v[206:209], v[90:93]
	v_mfma_f32_16x16x32_bf16 v[78:81], v[154:157], v[214:217], v[78:81]
	v_mfma_f32_16x16x32_bf16 v[74:77], v[166:169], v[214:217], v[74:77]
	s_nop 0
	s_nop 0
	v_mfma_f32_16x16x32_bf16 v[118:121], v[170:173], v[186:189], v[118:121]
	v_mfma_f32_16x16x32_bf16 v[114:117], v[178:181], v[186:189], v[114:117]
	v_mfma_f32_16x16x32_bf16 v[102:105], v[170:173], v[194:197], v[102:105]
	v_mfma_f32_16x16x32_bf16 v[98:101], v[178:181], v[194:197], v[98:101]
	v_mfma_f32_16x16x32_bf16 v[86:89], v[170:173], v[202:205], v[86:89]
	v_mfma_f32_16x16x32_bf16 v[82:85], v[178:181], v[202:205], v[82:85]
	v_mfma_f32_16x16x32_bf16 v[70:73], v[170:173], v[210:213], v[70:73]
	v_mfma_f32_16x16x32_bf16 v[66:69], v[178:181], v[210:213], v[66:69]
	v_mfma_f32_16x16x32_bf16 v[118:121], v[174:177], v[190:193], v[118:121]
	v_mfma_f32_16x16x32_bf16 v[114:117], v[182:185], v[190:193], v[114:117]
	v_mfma_f32_16x16x32_bf16 v[102:105], v[174:177], v[198:201], v[102:105]
	v_mfma_f32_16x16x32_bf16 v[98:101], v[182:185], v[198:201], v[98:101]
	v_mfma_f32_16x16x32_bf16 v[86:89], v[174:177], v[206:209], v[86:89]
	v_mfma_f32_16x16x32_bf16 v[82:85], v[182:185], v[206:209], v[82:85]
	v_mfma_f32_16x16x32_bf16 v[70:73], v[174:177], v[214:217], v[70:73]
	v_mfma_f32_16x16x32_bf16 v[66:69], v[182:185], v[214:217], v[66:69]
	s_nop 0
	s_barrier
	s_add_i32 s52, s46, s2
	v_lshl_add_u64 v[162:163], s[30:31], 0, v[132:133]
	s_mov_b32 m0, s52
	ds_read_b128 v[186:189], v151 offset:16384
	ds_read_b128 v[190:193], v151 offset:17408
	ds_read_b128 v[194:197], v151 offset:18432
	ds_read_b128 v[198:201], v151 offset:19456
	ds_read_b128 v[202:205], v151 offset:20480
	ds_read_b128 v[206:209], v151 offset:21504
	ds_read_b128 v[210:213], v151 offset:22528
	ds_read_b128 v[214:217], v151 offset:23552
	global_load_lds_dwordx4 v[162:163], off
	s_add_i32 m0, s52, 0x2000
	s_add_u32 s52, s30, 0x20000
	v_lshl_add_u64 v[218:219], s[30:31], 0, v[136:137]
	s_addc_u32 s53, s31, 0
	s_add_i32 s54, s47, s2
	global_load_lds_dwordx4 v[218:219], off
	v_lshl_add_u64 v[220:221], s[52:53], 0, v[132:133]
	s_mov_b32 m0, s54
	v_lshl_add_u64 v[222:223], s[34:35], 0, v[134:135]
	global_load_lds_dwordx4 v[220:221], off
	v_lshl_add_u64 v[220:221], s[52:53], 0, v[136:137]
	s_add_i32 m0, s54, 0x2000
	s_nop 0
	global_load_lds_dwordx4 v[220:221], off
	v_lshl_add_u64 v[220:221], s[34:35], 0, v[130:131]
	s_mov_b32 m0, s27
	s_nop 0
	global_load_lds_dwordx4 v[220:221], off
	s_mov_b32 m0, s37
	s_nop 0
	global_load_lds_dwordx4 v[222:223], off
	s_waitcnt vmcnt(8)
	s_waitcnt lgkmcnt(0)
	s_barrier
	s_nop 0
	s_waitcnt lgkmcnt(0)
	v_mfma_f32_16x16x32_bf16 v[62:65], v[142:145], v[186:189], v[62:65]
	v_mfma_f32_16x16x32_bf16 v[58:61], v[158:161], v[186:189], v[58:61]
	v_mfma_f32_16x16x32_bf16 v[46:49], v[142:145], v[194:197], v[46:49]
	v_mfma_f32_16x16x32_bf16 v[42:45], v[158:161], v[194:197], v[42:45]
	v_mfma_f32_16x16x32_bf16 v[30:33], v[142:145], v[202:205], v[30:33]
	v_mfma_f32_16x16x32_bf16 v[26:29], v[158:161], v[202:205], v[26:29]
	v_mfma_f32_16x16x32_bf16 v[14:17], v[142:145], v[210:213], v[14:17]
	v_mfma_f32_16x16x32_bf16 v[10:13], v[158:161], v[210:213], v[10:13]
	v_mfma_f32_16x16x32_bf16 v[62:65], v[154:157], v[190:193], v[62:65]
	v_mfma_f32_16x16x32_bf16 v[58:61], v[166:169], v[190:193], v[58:61]
	v_mfma_f32_16x16x32_bf16 v[46:49], v[154:157], v[198:201], v[46:49]
	v_mfma_f32_16x16x32_bf16 v[42:45], v[166:169], v[198:201], v[42:45]
	v_mfma_f32_16x16x32_bf16 v[30:33], v[154:157], v[206:209], v[30:33]
	v_mfma_f32_16x16x32_bf16 v[26:29], v[166:169], v[206:209], v[26:29]
	v_mfma_f32_16x16x32_bf16 v[14:17], v[154:157], v[214:217], v[14:17]
	v_mfma_f32_16x16x32_bf16 v[10:13], v[166:169], v[214:217], v[10:13]
	s_nop 0
	s_nop 0
	v_mfma_f32_16x16x32_bf16 v[54:57], v[170:173], v[186:189], v[54:57]
	v_mfma_f32_16x16x32_bf16 v[50:53], v[178:181], v[186:189], v[50:53]
	v_mfma_f32_16x16x32_bf16 v[38:41], v[170:173], v[194:197], v[38:41]
	v_mfma_f32_16x16x32_bf16 v[34:37], v[178:181], v[194:197], v[34:37]
	v_mfma_f32_16x16x32_bf16 v[22:25], v[170:173], v[202:205], v[22:25]
	v_mfma_f32_16x16x32_bf16 v[18:21], v[178:181], v[202:205], v[18:21]
	v_mfma_f32_16x16x32_bf16 v[6:9], v[170:173], v[210:213], v[6:9]
	v_mfma_f32_16x16x32_bf16 v[2:5], v[178:181], v[210:213], v[2:5]
	v_mfma_f32_16x16x32_bf16 v[54:57], v[174:177], v[190:193], v[54:57]
	v_mfma_f32_16x16x32_bf16 v[50:53], v[182:185], v[190:193], v[50:53]
	v_mfma_f32_16x16x32_bf16 v[38:41], v[174:177], v[198:201], v[38:41]
	v_mfma_f32_16x16x32_bf16 v[34:37], v[182:185], v[198:201], v[34:37]
	v_mfma_f32_16x16x32_bf16 v[22:25], v[174:177], v[206:209], v[22:25]
	v_mfma_f32_16x16x32_bf16 v[18:21], v[182:185], v[206:209], v[18:21]
	v_mfma_f32_16x16x32_bf16 v[6:9], v[174:177], v[214:217], v[6:9]
	v_mfma_f32_16x16x32_bf16 v[2:5], v[182:185], v[214:217], v[2:5]
	s_nop 0
	s_barrier
	s_add_i32 s52, 0, 0x18000
	v_add_u32_e32 v153, s52, v148
	s_add_i32 s53, 0, 0x1c000
	ds_read_b128 v[142:145], v153
	ds_read_b128 v[154:157], v153 offset:1024
	ds_read_b128 v[158:161], v153 offset:2048
	ds_read_b128 v[166:169], v153 offset:3072
	v_add_u32_e32 v153, s53, v148
	ds_read_b128 v[170:173], v153
	ds_read_b128 v[174:177], v153 offset:1024
	ds_read_b128 v[178:181], v153 offset:2048
	ds_read_b128 v[182:185], v153 offset:3072
	s_add_u32 s34, s34, 0x20000
	s_addc_u32 s35, s35, 0
	s_mov_b32 m0, s38
	v_lshl_add_u64 v[224:225], s[34:35], 0, v[130:131]
	ds_read_b128 v[186:189], v151 offset:32768
	ds_read_b128 v[190:193], v151 offset:33792
	ds_read_b128 v[194:197], v151 offset:34816
	ds_read_b128 v[198:201], v151 offset:35840
	ds_read_b128 v[202:205], v151 offset:36864
	ds_read_b128 v[206:209], v151 offset:37888
	ds_read_b128 v[210:213], v151 offset:38912
	ds_read_b128 v[214:217], v151 offset:39936
	global_load_lds_dwordx4 v[224:225], off
	v_lshl_add_u64 v[224:225], s[34:35], 0, v[134:135]
	s_mov_b32 m0, s39
	s_nop 0
	global_load_lds_dwordx4 v[224:225], off
	s_waitcnt vmcnt(8)
	s_waitcnt lgkmcnt(0)
	s_barrier
	s_nop 0
	s_waitcnt lgkmcnt(0)
	v_mfma_f32_16x16x32_bf16 v[126:129], v[142:145], v[186:189], v[126:129]
	v_mfma_f32_16x16x32_bf16 v[122:125], v[158:161], v[186:189], v[122:125]
	v_mfma_f32_16x16x32_bf16 v[110:113], v[142:145], v[194:197], v[110:113]
	v_mfma_f32_16x16x32_bf16 v[106:109], v[158:161], v[194:197], v[106:109]
	v_mfma_f32_16x16x32_bf16 v[94:97], v[142:145], v[202:205], v[94:97]
	v_mfma_f32_16x16x32_bf16 v[90:93], v[158:161], v[202:205], v[90:93]
	v_mfma_f32_16x16x32_bf16 v[78:81], v[142:145], v[210:213], v[78:81]
	v_mfma_f32_16x16x32_bf16 v[74:77], v[158:161], v[210:213], v[74:77]
	v_mfma_f32_16x16x32_bf16 v[126:129], v[154:157], v[190:193], v[126:129]
	v_mfma_f32_16x16x32_bf16 v[122:125], v[166:169], v[190:193], v[122:125]
	v_mfma_f32_16x16x32_bf16 v[110:113], v[154:157], v[198:201], v[110:113]
	v_mfma_f32_16x16x32_bf16 v[106:109], v[166:169], v[198:201], v[106:109]
	v_mfma_f32_16x16x32_bf16 v[94:97], v[154:157], v[206:209], v[94:97]
	v_mfma_f32_16x16x32_bf16 v[90:93], v[166:169], v[206:209], v[90:93]
	v_mfma_f32_16x16x32_bf16 v[78:81], v[154:157], v[214:217], v[78:81]
	v_mfma_f32_16x16x32_bf16 v[74:77], v[166:169], v[214:217], v[74:77]
	s_nop 0
	s_nop 0
	v_mfma_f32_16x16x32_bf16 v[118:121], v[170:173], v[186:189], v[118:121]
	v_mfma_f32_16x16x32_bf16 v[114:117], v[178:181], v[186:189], v[114:117]
	v_mfma_f32_16x16x32_bf16 v[102:105], v[170:173], v[194:197], v[102:105]
	v_mfma_f32_16x16x32_bf16 v[98:101], v[178:181], v[194:197], v[98:101]
	v_mfma_f32_16x16x32_bf16 v[86:89], v[170:173], v[202:205], v[86:89]
	v_mfma_f32_16x16x32_bf16 v[82:85], v[178:181], v[202:205], v[82:85]
	v_mfma_f32_16x16x32_bf16 v[70:73], v[170:173], v[210:213], v[70:73]
	v_mfma_f32_16x16x32_bf16 v[66:69], v[178:181], v[210:213], v[66:69]
	v_mfma_f32_16x16x32_bf16 v[118:121], v[174:177], v[190:193], v[118:121]
	v_mfma_f32_16x16x32_bf16 v[114:117], v[182:185], v[190:193], v[114:117]
	v_mfma_f32_16x16x32_bf16 v[102:105], v[174:177], v[198:201], v[102:105]
	v_mfma_f32_16x16x32_bf16 v[98:101], v[182:185], v[198:201], v[98:101]
	v_mfma_f32_16x16x32_bf16 v[86:89], v[174:177], v[206:209], v[86:89]
	v_mfma_f32_16x16x32_bf16 v[82:85], v[182:185], v[206:209], v[82:85]
	v_mfma_f32_16x16x32_bf16 v[70:73], v[174:177], v[214:217], v[70:73]
	v_mfma_f32_16x16x32_bf16 v[66:69], v[182:185], v[214:217], v[66:69]
	s_nop 0
	s_barrier
	s_add_i32 s34, s52, s2
	v_lshl_add_u64 v[162:163], v[162:163], 0, s[10:11]
	s_mov_b32 m0, s34
	ds_read_b128 v[186:189], v151 offset:49152
	ds_read_b128 v[190:193], v151 offset:50176
	ds_read_b128 v[194:197], v151 offset:51200
	ds_read_b128 v[198:201], v151 offset:52224
	ds_read_b128 v[202:205], v151 offset:53248
	ds_read_b128 v[206:209], v151 offset:54272
	ds_read_b128 v[210:213], v151 offset:55296
	ds_read_b128 v[214:217], v151 offset:56320
	global_load_lds_dwordx4 v[162:163], off
	s_add_i32 m0, s34, 0x2000
	s_add_u32 s30, s30, 0x20080
	v_lshl_add_u64 v[162:163], v[218:219], 0, s[10:11]
	s_addc_u32 s31, s31, 0
	s_add_i32 s34, s53, s2
	global_load_lds_dwordx4 v[162:163], off
	v_lshl_add_u64 v[162:163], s[30:31], 0, v[132:133]
	s_mov_b32 m0, s34
	s_nop 0
	global_load_lds_dwordx4 v[162:163], off
	v_lshl_add_u64 v[162:163], s[30:31], 0, v[136:137]
	s_add_i32 m0, s34, 0x2000
	s_nop 0
	global_load_lds_dwordx4 v[162:163], off
	v_lshl_add_u64 v[162:163], v[220:221], 0, s[10:11]
	s_mov_b32 m0, s43
	s_nop 0
	global_load_lds_dwordx4 v[162:163], off
	v_lshl_add_u64 v[162:163], v[222:223], 0, s[10:11]
	s_mov_b32 m0, s44
	s_nop 0
	global_load_lds_dwordx4 v[162:163], off
	s_waitcnt vmcnt(8)
	s_waitcnt lgkmcnt(0)
	s_barrier
	s_nop 0
	s_waitcnt lgkmcnt(0)
	v_mfma_f32_16x16x32_bf16 v[62:65], v[142:145], v[186:189], v[62:65]
	v_mfma_f32_16x16x32_bf16 v[58:61], v[158:161], v[186:189], v[58:61]
	v_mfma_f32_16x16x32_bf16 v[46:49], v[142:145], v[194:197], v[46:49]
	v_mfma_f32_16x16x32_bf16 v[42:45], v[158:161], v[194:197], v[42:45]
	v_mfma_f32_16x16x32_bf16 v[30:33], v[142:145], v[202:205], v[30:33]
	v_mfma_f32_16x16x32_bf16 v[26:29], v[158:161], v[202:205], v[26:29]
	v_mfma_f32_16x16x32_bf16 v[14:17], v[142:145], v[210:213], v[14:17]
	v_mfma_f32_16x16x32_bf16 v[10:13], v[158:161], v[210:213], v[10:13]
	v_mfma_f32_16x16x32_bf16 v[62:65], v[154:157], v[190:193], v[62:65]
	v_mfma_f32_16x16x32_bf16 v[58:61], v[166:169], v[190:193], v[58:61]
	v_mfma_f32_16x16x32_bf16 v[46:49], v[154:157], v[198:201], v[46:49]
	v_mfma_f32_16x16x32_bf16 v[42:45], v[166:169], v[198:201], v[42:45]
	v_mfma_f32_16x16x32_bf16 v[30:33], v[154:157], v[206:209], v[30:33]
	v_mfma_f32_16x16x32_bf16 v[26:29], v[166:169], v[206:209], v[26:29]
	v_mfma_f32_16x16x32_bf16 v[14:17], v[154:157], v[214:217], v[14:17]
	v_mfma_f32_16x16x32_bf16 v[10:13], v[166:169], v[214:217], v[10:13]
	s_nop 0
	s_nop 0
	v_mfma_f32_16x16x32_bf16 v[54:57], v[170:173], v[186:189], v[54:57]
	v_mfma_f32_16x16x32_bf16 v[50:53], v[178:181], v[186:189], v[50:53]
	v_mfma_f32_16x16x32_bf16 v[38:41], v[170:173], v[194:197], v[38:41]
	v_mfma_f32_16x16x32_bf16 v[34:37], v[178:181], v[194:197], v[34:37]
	v_mfma_f32_16x16x32_bf16 v[22:25], v[170:173], v[202:205], v[22:25]
	v_mfma_f32_16x16x32_bf16 v[18:21], v[178:181], v[202:205], v[18:21]
	v_mfma_f32_16x16x32_bf16 v[6:9], v[170:173], v[210:213], v[6:9]
	v_mfma_f32_16x16x32_bf16 v[2:5], v[178:181], v[210:213], v[2:5]
	v_mfma_f32_16x16x32_bf16 v[54:57], v[174:177], v[190:193], v[54:57]
	v_mfma_f32_16x16x32_bf16 v[50:53], v[182:185], v[190:193], v[50:53]
	v_mfma_f32_16x16x32_bf16 v[38:41], v[174:177], v[198:201], v[38:41]
	v_mfma_f32_16x16x32_bf16 v[34:37], v[182:185], v[198:201], v[34:37]
	v_mfma_f32_16x16x32_bf16 v[22:25], v[174:177], v[206:209], v[22:25]
	v_mfma_f32_16x16x32_bf16 v[18:21], v[182:185], v[206:209], v[18:21]
	v_mfma_f32_16x16x32_bf16 v[6:9], v[174:177], v[214:217], v[6:9]
	v_mfma_f32_16x16x32_bf16 v[2:5], v[182:185], v[214:217], v[2:5]
	s_nop 0
	s_barrier
	s_add_i32 s51, s51, 2
	s_add_u32 s28, s28, 0x100
	s_addc_u32 s29, s29, 0
	s_add_u32 s49, s49, 0x100
	s_addc_u32 s50, s50, 0
	s_cmp_gt_u32 s51, 5
	s_cbranch_scc0 .LBB0_1220
	s_setprio 0
	s_lshl_b32 s98, s26, 8
	s_add_i32 s98, s98, s41
	v_add_u32_e32 v240, s98, v146
	s_lshl_b32 s98, s0, 8
	s_or_b32 s98, s98, s42
	v_lshl_add_u32 v241, v147, 3, s98
	v_lshlrev_b32_e32 v240, 12, v240
	v_lshl_add_u32 v240, v241, 1, v240
	global_load_dwordx4 v[168:171], v240, s[62:63]
	global_load_dwordx4 v[172:175], v240, s[62:63] offset:256
	v_add_u32_e32 v240, 0x10000, v240
	global_load_dwordx4 v[176:179], v240, s[62:63]
	global_load_dwordx4 v[180:183], v240, s[62:63] offset:256
	v_add_u32_e32 v240, 0x10000, v240
	global_load_dwordx4 v[184:187], v240, s[62:63]
	global_load_dwordx4 v[188:191], v240, s[62:63] offset:256
	v_add_u32_e32 v240, 0x10000, v240
	global_load_dwordx4 v[192:195], v240, s[62:63]
	global_load_dwordx4 v[196:199], v240, s[62:63] offset:256
	v_add_u32_e32 v240, 0x50000, v240
	global_load_dwordx4 v[200:203], v240, s[62:63]
	global_load_dwordx4 v[204:207], v240, s[62:63] offset:256
	v_add_u32_e32 v240, 0x10000, v240
	global_load_dwordx4 v[208:211], v240, s[62:63]
	global_load_dwordx4 v[212:215], v240, s[62:63] offset:256
	v_add_u32_e32 v240, 0x10000, v240
	global_load_dwordx4 v[216:219], v240, s[62:63]
	global_load_dwordx4 v[220:223], v240, s[62:63] offset:256
	v_add_u32_e32 v240, 0x10000, v240
	global_load_dwordx4 v[224:227], v240, s[62:63]
	global_load_dwordx4 v[232:235], v240, s[62:63] offset:256
	s_and_b64 vcc, exec, s[12:13]
	s_cbranch_vccz .LBB0_1223
	s_barrier

.LBB0_1448:
	s_and_b64 s[22:23], s[18:19], exec
	s_cselect_b32 s25, s15, s1
	s_cselect_b32 s47, s14, s0
	s_cselect_b32 s48, s17, s21
	s_cselect_b32 s49, s16, s20
	s_add_u32 s0, s0, 0x160080
	s_addc_u32 s1, s1, 0
	s_add_u32 s50, s20, 0x100
	v_mov_b32_e32 v0, 0
	s_addc_u32 s51, s21, 0
	s_mov_b32 s52, -2
	v_mov_b32_e32 v1, v0
	v_mov_b32_e32 v2, v0
	v_mov_b32_e32 v3, v0
	v_mov_b32_e32 v4, v0
	v_mov_b32_e32 v5, v0
	v_mov_b32_e32 v6, v0
	v_mov_b32_e32 v7, v0
	v_mov_b32_e32 v16, v0
	v_mov_b32_e32 v17, v0
	v_mov_b32_e32 v18, v0
	v_mov_b32_e32 v19, v0
	v_mov_b32_e32 v20, v0
	v_mov_b32_e32 v21, v0
	v_mov_b32_e32 v22, v0
	v_mov_b32_e32 v23, v0
	v_mov_b32_e32 v32, v0
	v_mov_b32_e32 v33, v0
	v_mov_b32_e32 v34, v0
	v_mov_b32_e32 v35, v0
	v_mov_b32_e32 v36, v0
	v_mov_b32_e32 v37, v0
	v_mov_b32_e32 v38, v0
	v_mov_b32_e32 v39, v0
	v_mov_b32_e32 v48, v0
	v_mov_b32_e32 v49, v0
	v_mov_b32_e32 v50, v0
	v_mov_b32_e32 v51, v0
	v_mov_b32_e32 v52, v0
	v_mov_b32_e32 v53, v0
	v_mov_b32_e32 v54, v0
	v_mov_b32_e32 v55, v0
	v_mov_b32_e32 v8, v0
	v_mov_b32_e32 v9, v0
	v_mov_b32_e32 v10, v0
	v_mov_b32_e32 v11, v0
	v_mov_b32_e32 v12, v0
	v_mov_b32_e32 v13, v0
	v_mov_b32_e32 v14, v0
	v_mov_b32_e32 v15, v0
	v_mov_b32_e32 v24, v0
	v_mov_b32_e32 v25, v0
	v_mov_b32_e32 v26, v0
	v_mov_b32_e32 v27, v0
	v_mov_b32_e32 v28, v0
	v_mov_b32_e32 v29, v0
	v_mov_b32_e32 v30, v0
	v_mov_b32_e32 v31, v0
	v_mov_b32_e32 v40, v0
	v_mov_b32_e32 v41, v0
	v_mov_b32_e32 v42, v0
	v_mov_b32_e32 v43, v0
	v_mov_b32_e32 v44, v0
	v_mov_b32_e32 v45, v0
	v_mov_b32_e32 v46, v0
	v_mov_b32_e32 v47, v0
	v_mov_b32_e32 v56, v0
	v_mov_b32_e32 v57, v0
	v_mov_b32_e32 v58, v0
	v_mov_b32_e32 v59, v0
	v_mov_b32_e32 v60, v0
	v_mov_b32_e32 v61, v0
	v_mov_b32_e32 v62, v0
	v_mov_b32_e32 v63, v0
	v_mov_b32_e32 v64, v0
	v_mov_b32_e32 v65, v0
	v_mov_b32_e32 v66, v0
	v_mov_b32_e32 v67, v0
	v_mov_b32_e32 v68, v0
	v_mov_b32_e32 v69, v0
	v_mov_b32_e32 v70, v0
	v_mov_b32_e32 v71, v0
	v_mov_b32_e32 v80, v0
	v_mov_b32_e32 v81, v0
	v_mov_b32_e32 v82, v0
	v_mov_b32_e32 v83, v0
	v_mov_b32_e32 v84, v0
	v_mov_b32_e32 v85, v0
	v_mov_b32_e32 v86, v0
	v_mov_b32_e32 v87, v0
	v_mov_b32_e32 v96, v0
	v_mov_b32_e32 v97, v0
	v_mov_b32_e32 v98, v0
	v_mov_b32_e32 v99, v0
	v_mov_b32_e32 v100, v0
	v_mov_b32_e32 v101, v0
	v_mov_b32_e32 v102, v0
	v_mov_b32_e32 v103, v0
	v_mov_b32_e32 v112, v0
	v_mov_b32_e32 v113, v0
	v_mov_b32_e32 v114, v0
	v_mov_b32_e32 v115, v0
	v_mov_b32_e32 v116, v0
	v_mov_b32_e32 v117, v0
	v_mov_b32_e32 v118, v0
	v_mov_b32_e32 v119, v0
	v_mov_b32_e32 v72, v0
	v_mov_b32_e32 v73, v0
	v_mov_b32_e32 v74, v0
	v_mov_b32_e32 v75, v0
	v_mov_b32_e32 v76, v0
	v_mov_b32_e32 v77, v0
	v_mov_b32_e32 v78, v0
	v_mov_b32_e32 v79, v0
	v_mov_b32_e32 v88, v0
	v_mov_b32_e32 v89, v0
	v_mov_b32_e32 v90, v0
	v_mov_b32_e32 v91, v0
	v_mov_b32_e32 v92, v0
	v_mov_b32_e32 v93, v0
	v_mov_b32_e32 v94, v0
	v_mov_b32_e32 v95, v0
	v_mov_b32_e32 v104, v0
	v_mov_b32_e32 v105, v0
	v_mov_b32_e32 v106, v0
	v_mov_b32_e32 v107, v0
	v_mov_b32_e32 v108, v0
	v_mov_b32_e32 v109, v0
	v_mov_b32_e32 v110, v0
	v_mov_b32_e32 v111, v0
	v_mov_b32_e32 v120, v0
	v_mov_b32_e32 v121, v0
	v_mov_b32_e32 v122, v0
	v_mov_b32_e32 v123, v0
	v_mov_b32_e32 v124, v0
	v_mov_b32_e32 v125, v0
	v_mov_b32_e32 v126, v0
	v_mov_b32_e32 v127, v0
	s_and_b64 s[98:99], exec, s[10:11]
	s_cbranch_scc1 .Lsp_p11
	s_setprio 1
.Lsp_p11:
.LBB0_1449:
	ds_read_b128 v[140:143], v167
	ds_read_b128 v[144:147], v167 offset:1024
	ds_read_b128 v[148:151], v167 offset:2048
	ds_read_b128 v[152:155], v167 offset:3072
	ds_read_b128 v[156:159], v168
	ds_read_b128 v[172:175], v168 offset:1024
	ds_read_b128 v[176:179], v168 offset:2048
	ds_read_b128 v[180:183], v168 offset:3072
	s_add_u32 s20, s0, 0xffea0080
	s_addc_u32 s21, s1, -1
	s_cmpk_eq_i32 s52, 0x54
	s_cselect_b32 s23, s25, s21
	s_cselect_b32 s22, s47, s20
	s_cselect_b32 s21, s48, s51
	s_cselect_b32 s20, s49, s50
	v_lshl_add_u64 v[160:161], s[0:1], 0, v[136:137]
	s_add_i32 m0, s29, 0xc000
	ds_read_b128 v[184:187], v169
	ds_read_b128 v[188:191], v169 offset:1024
	ds_read_b128 v[192:195], v169 offset:2048
	ds_read_b128 v[196:199], v169 offset:3072
	ds_read_b128 v[200:203], v169 offset:4096
	ds_read_b128 v[204:207], v169 offset:5120
	ds_read_b128 v[208:211], v169 offset:6144
	ds_read_b128 v[212:215], v169 offset:7168
	global_load_lds_dwordx4 v[160:161], off
	v_lshl_add_u64 v[160:161], s[0:1], 0, v[138:139]
	s_add_i32 m0, s29, 0xe000
	s_nop 0
	global_load_lds_dwordx4 v[160:161], off
	s_waitcnt vmcnt(8)
	s_waitcnt lgkmcnt(0)
	s_barrier
	s_nop 0
	s_waitcnt lgkmcnt(0)
	v_mfma_f32_16x16x32_bf16 v[124:127], v[140:143], v[184:187], v[124:127]
	v_mfma_f32_16x16x32_bf16 v[120:123], v[148:151], v[184:187], v[120:123]
	v_mfma_f32_16x16x32_bf16 v[108:111], v[140:143], v[192:195], v[108:111]
	v_mfma_f32_16x16x32_bf16 v[104:107], v[148:151], v[192:195], v[104:107]
	v_mfma_f32_16x16x32_bf16 v[92:95], v[140:143], v[200:203], v[92:95]
	v_mfma_f32_16x16x32_bf16 v[88:91], v[148:151], v[200:203], v[88:91]
	v_mfma_f32_16x16x32_bf16 v[76:79], v[140:143], v[208:211], v[76:79]
	v_mfma_f32_16x16x32_bf16 v[72:75], v[148:151], v[208:211], v[72:75]
	v_mfma_f32_16x16x32_bf16 v[124:127], v[144:147], v[188:191], v[124:127]
	v_mfma_f32_16x16x32_bf16 v[120:123], v[152:155], v[188:191], v[120:123]
	v_mfma_f32_16x16x32_bf16 v[108:111], v[144:147], v[196:199], v[108:111]
	v_mfma_f32_16x16x32_bf16 v[104:107], v[152:155], v[196:199], v[104:107]
	v_mfma_f32_16x16x32_bf16 v[92:95], v[144:147], v[204:207], v[92:95]
	v_mfma_f32_16x16x32_bf16 v[88:91], v[152:155], v[204:207], v[88:91]
	v_mfma_f32_16x16x32_bf16 v[76:79], v[144:147], v[212:215], v[76:79]
	v_mfma_f32_16x16x32_bf16 v[72:75], v[152:155], v[212:215], v[72:75]
	s_nop 0
	s_nop 0
	v_mfma_f32_16x16x32_bf16 v[116:119], v[156:159], v[184:187], v[116:119]
	v_mfma_f32_16x16x32_bf16 v[112:115], v[176:179], v[184:187], v[112:115]
	v_mfma_f32_16x16x32_bf16 v[100:103], v[156:159], v[192:195], v[100:103]
	v_mfma_f32_16x16x32_bf16 v[96:99], v[176:179], v[192:195], v[96:99]
	v_mfma_f32_16x16x32_bf16 v[84:87], v[156:159], v[200:203], v[84:87]
	v_mfma_f32_16x16x32_bf16 v[80:83], v[176:179], v[200:203], v[80:83]
	v_mfma_f32_16x16x32_bf16 v[68:71], v[156:159], v[208:211], v[68:71]
	v_mfma_f32_16x16x32_bf16 v[64:67], v[176:179], v[208:211], v[64:67]
	v_mfma_f32_16x16x32_bf16 v[116:119], v[172:175], v[188:191], v[116:119]
	v_mfma_f32_16x16x32_bf16 v[112:115], v[180:183], v[188:191], v[112:115]
	v_mfma_f32_16x16x32_bf16 v[100:103], v[172:175], v[196:199], v[100:103]
	v_mfma_f32_16x16x32_bf16 v[96:99], v[180:183], v[196:199], v[96:99]
	v_mfma_f32_16x16x32_bf16 v[84:87], v[172:175], v[204:207], v[84:87]
	v_mfma_f32_16x16x32_bf16 v[80:83], v[180:183], v[204:207], v[80:83]
	v_mfma_f32_16x16x32_bf16 v[68:71], v[172:175], v[212:215], v[68:71]
	v_mfma_f32_16x16x32_bf16 v[64:67], v[180:183], v[212:215], v[64:67]
	s_nop 0
	s_barrier
	s_add_i32 s53, s42, s28
	v_lshl_add_u64 v[160:161], s[20:21], 0, v[130:131]
	s_mov_b32 m0, s53
	ds_read_b128 v[184:187], v169 offset:16384
	ds_read_b128 v[188:191], v169 offset:17408
	ds_read_b128 v[192:195], v169 offset:18432
	ds_read_b128 v[196:199], v169 offset:19456
	ds_read_b128 v[200:203], v169 offset:20480
	ds_read_b128 v[204:207], v169 offset:21504
	ds_read_b128 v[208:211], v169 offset:22528
	ds_read_b128 v[212:215], v169 offset:23552
	global_load_lds_dwordx4 v[160:161], off
	s_add_i32 m0, s53, 0x2000
	s_add_u32 s54, s20, 0x160000
	v_lshl_add_u64 v[216:217], s[20:21], 0, v[134:135]
	s_addc_u32 s55, s21, 0
	s_add_i32 s53, s43, s28
	global_load_lds_dwordx4 v[216:217], off
	v_lshl_add_u64 v[218:219], s[54:55], 0, v[130:131]
	s_mov_b32 m0, s53
	v_lshl_add_u64 v[220:221], s[22:23], 0, v[132:133]
	global_load_lds_dwordx4 v[218:219], off
	v_lshl_add_u64 v[218:219], s[54:55], 0, v[134:135]
	s_add_i32 m0, s53, 0x2000
	s_nop 0
	global_load_lds_dwordx4 v[218:219], off
	v_lshl_add_u64 v[218:219], s[22:23], 0, v[128:129]
	s_mov_b32 m0, s29
	s_nop 0
	global_load_lds_dwordx4 v[218:219], off
	s_mov_b32 m0, s30
	s_nop 0
	global_load_lds_dwordx4 v[220:221], off
	s_waitcnt vmcnt(8)
	s_waitcnt lgkmcnt(0)
	s_barrier
	s_nop 0
	s_waitcnt lgkmcnt(0)
	v_mfma_f32_16x16x32_bf16 v[60:63], v[140:143], v[184:187], v[60:63]
	v_mfma_f32_16x16x32_bf16 v[56:59], v[148:151], v[184:187], v[56:59]
	v_mfma_f32_16x16x32_bf16 v[44:47], v[140:143], v[192:195], v[44:47]
	v_mfma_f32_16x16x32_bf16 v[40:43], v[148:151], v[192:195], v[40:43]
	v_mfma_f32_16x16x32_bf16 v[28:31], v[140:143], v[200:203], v[28:31]
	v_mfma_f32_16x16x32_bf16 v[24:27], v[148:151], v[200:203], v[24:27]
	v_mfma_f32_16x16x32_bf16 v[12:15], v[140:143], v[208:211], v[12:15]
	v_mfma_f32_16x16x32_bf16 v[8:11], v[148:151], v[208:211], v[8:11]
	v_mfma_f32_16x16x32_bf16 v[60:63], v[144:147], v[188:191], v[60:63]
	v_mfma_f32_16x16x32_bf16 v[56:59], v[152:155], v[188:191], v[56:59]
	v_mfma_f32_16x16x32_bf16 v[44:47], v[144:147], v[196:199], v[44:47]
	v_mfma_f32_16x16x32_bf16 v[40:43], v[152:155], v[196:199], v[40:43]
	v_mfma_f32_16x16x32_bf16 v[28:31], v[144:147], v[204:207], v[28:31]
	v_mfma_f32_16x16x32_bf16 v[24:27], v[152:155], v[204:207], v[24:27]
	v_mfma_f32_16x16x32_bf16 v[12:15], v[144:147], v[212:215], v[12:15]
	v_mfma_f32_16x16x32_bf16 v[8:11], v[152:155], v[212:215], v[8:11]
	s_nop 0
	s_nop 0
	v_mfma_f32_16x16x32_bf16 v[52:55], v[156:159], v[184:187], v[52:55]
	v_mfma_f32_16x16x32_bf16 v[48:51], v[176:179], v[184:187], v[48:51]
	v_mfma_f32_16x16x32_bf16 v[36:39], v[156:159], v[192:195], v[36:39]
	v_mfma_f32_16x16x32_bf16 v[32:35], v[176:179], v[192:195], v[32:35]
	v_mfma_f32_16x16x32_bf16 v[20:23], v[156:159], v[200:203], v[20:23]
	v_mfma_f32_16x16x32_bf16 v[16:19], v[176:179], v[200:203], v[16:19]
	v_mfma_f32_16x16x32_bf16 v[4:7], v[156:159], v[208:211], v[4:7]
	v_mfma_f32_16x16x32_bf16 v[0:3], v[176:179], v[208:211], v[0:3]
	v_mfma_f32_16x16x32_bf16 v[52:55], v[172:175], v[188:191], v[52:55]
	v_mfma_f32_16x16x32_bf16 v[48:51], v[180:183], v[188:191], v[48:51]
	v_mfma_f32_16x16x32_bf16 v[36:39], v[172:175], v[196:199], v[36:39]
	v_mfma_f32_16x16x32_bf16 v[32:35], v[180:183], v[196:199], v[32:35]
	v_mfma_f32_16x16x32_bf16 v[20:23], v[172:175], v[204:207], v[20:23]
	v_mfma_f32_16x16x32_bf16 v[16:19], v[180:183], v[204:207], v[16:19]
	v_mfma_f32_16x16x32_bf16 v[4:7], v[172:175], v[212:215], v[4:7]
	v_mfma_f32_16x16x32_bf16 v[0:3], v[180:183], v[212:215], v[0:3]
	s_nop 0
	s_barrier
	s_add_i32 s53, 0, 0x18000
	s_add_i32 s54, 0, 0x1c000
	v_add_u32_e32 v152, s53, v166
	v_add_u32_e32 v180, s54, v166
	ds_read_b128 v[140:143], v152
	ds_read_b128 v[144:147], v152 offset:1024
	ds_read_b128 v[148:151], v152 offset:2048
	ds_read_b128 v[152:155], v152 offset:3072
	ds_read_b128 v[156:159], v180
	ds_read_b128 v[172:175], v180 offset:1024
	ds_read_b128 v[176:179], v180 offset:2048
	ds_read_b128 v[180:183], v180 offset:3072
	s_add_u32 s22, s22, 0x160000
	s_addc_u32 s23, s23, 0
	s_mov_b32 m0, s31
	v_lshl_add_u64 v[222:223], s[22:23], 0, v[128:129]
	ds_read_b128 v[184:187], v169 offset:32768
	ds_read_b128 v[188:191], v169 offset:33792
	ds_read_b128 v[192:195], v169 offset:34816
	ds_read_b128 v[196:199], v169 offset:35840
	ds_read_b128 v[200:203], v169 offset:36864
	ds_read_b128 v[204:207], v169 offset:37888
	ds_read_b128 v[208:211], v169 offset:38912
	ds_read_b128 v[212:215], v169 offset:39936
	global_load_lds_dwordx4 v[222:223], off
	v_lshl_add_u64 v[222:223], s[22:23], 0, v[132:133]
	s_mov_b32 m0, s33
	s_nop 0
	global_load_lds_dwordx4 v[222:223], off
	s_waitcnt vmcnt(8)
	s_waitcnt lgkmcnt(0)
	s_barrier
	s_nop 0
	s_waitcnt lgkmcnt(0)
	v_mfma_f32_16x16x32_bf16 v[124:127], v[140:143], v[184:187], v[124:127]
	v_mfma_f32_16x16x32_bf16 v[120:123], v[148:151], v[184:187], v[120:123]
	v_mfma_f32_16x16x32_bf16 v[108:111], v[140:143], v[192:195], v[108:111]
	v_mfma_f32_16x16x32_bf16 v[104:107], v[148:151], v[192:195], v[104:107]
	v_mfma_f32_16x16x32_bf16 v[92:95], v[140:143], v[200:203], v[92:95]
	v_mfma_f32_16x16x32_bf16 v[88:91], v[148:151], v[200:203], v[88:91]
	v_mfma_f32_16x16x32_bf16 v[76:79], v[140:143], v[208:211], v[76:79]
	v_mfma_f32_16x16x32_bf16 v[72:75], v[148:151], v[208:211], v[72:75]
	v_mfma_f32_16x16x32_bf16 v[124:127], v[144:147], v[188:191], v[124:127]
	v_mfma_f32_16x16x32_bf16 v[120:123], v[152:155], v[188:191], v[120:123]
	v_mfma_f32_16x16x32_bf16 v[108:111], v[144:147], v[196:199], v[108:111]
	v_mfma_f32_16x16x32_bf16 v[104:107], v[152:155], v[196:199], v[104:107]
	v_mfma_f32_16x16x32_bf16 v[92:95], v[144:147], v[204:207], v[92:95]
	v_mfma_f32_16x16x32_bf16 v[88:91], v[152:155], v[204:207], v[88:91]
	v_mfma_f32_16x16x32_bf16 v[76:79], v[144:147], v[212:215], v[76:79]
	v_mfma_f32_16x16x32_bf16 v[72:75], v[152:155], v[212:215], v[72:75]
	s_nop 0
	s_nop 0
	v_mfma_f32_16x16x32_bf16 v[116:119], v[156:159], v[184:187], v[116:119]
	v_mfma_f32_16x16x32_bf16 v[112:115], v[176:179], v[184:187], v[112:115]
	v_mfma_f32_16x16x32_bf16 v[100:103], v[156:159], v[192:195], v[100:103]
	v_mfma_f32_16x16x32_bf16 v[96:99], v[176:179], v[192:195], v[96:99]
	v_mfma_f32_16x16x32_bf16 v[84:87], v[156:159], v[200:203], v[84:87]
	v_mfma_f32_16x16x32_bf16 v[80:83], v[176:179], v[200:203], v[80:83]
	v_mfma_f32_16x16x32_bf16 v[68:71], v[156:159], v[208:211], v[68:71]
	v_mfma_f32_16x16x32_bf16 v[64:67], v[176:179], v[208:211], v[64:67]
	v_mfma_f32_16x16x32_bf16 v[116:119], v[172:175], v[188:191], v[116:119]
	v_mfma_f32_16x16x32_bf16 v[112:115], v[180:183], v[188:191], v[112:115]
	v_mfma_f32_16x16x32_bf16 v[100:103], v[172:175], v[196:199], v[100:103]
	v_mfma_f32_16x16x32_bf16 v[96:99], v[180:183], v[196:199], v[96:99]
	v_mfma_f32_16x16x32_bf16 v[84:87], v[172:175], v[204:207], v[84:87]
	v_mfma_f32_16x16x32_bf16 v[80:83], v[180:183], v[204:207], v[80:83]
	v_mfma_f32_16x16x32_bf16 v[68:71], v[172:175], v[212:215], v[68:71]
	v_mfma_f32_16x16x32_bf16 v[64:67], v[180:183], v[212:215], v[64:67]
	s_nop 0
	s_barrier
	s_add_i32 s22, s53, s28
	v_lshl_add_u64 v[160:161], v[160:161], 0, s[8:9]
	s_mov_b32 m0, s22
	ds_read_b128 v[184:187], v169 offset:49152
	ds_read_b128 v[188:191], v169 offset:50176
	ds_read_b128 v[192:195], v169 offset:51200
	ds_read_b128 v[196:199], v169 offset:52224
	ds_read_b128 v[200:203], v169 offset:53248
	ds_read_b128 v[204:207], v169 offset:54272
	ds_read_b128 v[208:211], v169 offset:55296
	ds_read_b128 v[212:215], v169 offset:56320
	global_load_lds_dwordx4 v[160:161], off
	s_add_i32 m0, s22, 0x2000
	s_add_u32 s20, s20, 0x160080
	v_lshl_add_u64 v[160:161], v[216:217], 0, s[8:9]
	s_addc_u32 s21, s21, 0
	s_add_i32 s22, s54, s28
	global_load_lds_dwordx4 v[160:161], off
	v_lshl_add_u64 v[160:161], s[20:21], 0, v[130:131]
	s_mov_b32 m0, s22
	s_nop 0
	global_load_lds_dwordx4 v[160:161], off
	v_lshl_add_u64 v[160:161], s[20:21], 0, v[134:135]
	s_add_i32 m0, s22, 0x2000
	s_nop 0
	global_load_lds_dwordx4 v[160:161], off
	v_lshl_add_u64 v[160:161], v[218:219], 0, s[8:9]
	s_mov_b32 m0, s39
	s_nop 0
	global_load_lds_dwordx4 v[160:161], off
	v_lshl_add_u64 v[160:161], v[220:221], 0, s[8:9]
	s_mov_b32 m0, s40
	s_nop 0
	global_load_lds_dwordx4 v[160:161], off
	s_waitcnt vmcnt(8)
	s_waitcnt lgkmcnt(0)
	s_barrier
	s_nop 0
	s_waitcnt lgkmcnt(0)
	v_mfma_f32_16x16x32_bf16 v[60:63], v[140:143], v[184:187], v[60:63]
	v_mfma_f32_16x16x32_bf16 v[56:59], v[148:151], v[184:187], v[56:59]
	v_mfma_f32_16x16x32_bf16 v[44:47], v[140:143], v[192:195], v[44:47]
	v_mfma_f32_16x16x32_bf16 v[40:43], v[148:151], v[192:195], v[40:43]
	v_mfma_f32_16x16x32_bf16 v[28:31], v[140:143], v[200:203], v[28:31]
	v_mfma_f32_16x16x32_bf16 v[24:27], v[148:151], v[200:203], v[24:27]
	v_mfma_f32_16x16x32_bf16 v[12:15], v[140:143], v[208:211], v[12:15]
	v_mfma_f32_16x16x32_bf16 v[8:11], v[148:151], v[208:211], v[8:11]
	v_mfma_f32_16x16x32_bf16 v[60:63], v[144:147], v[188:191], v[60:63]
	v_mfma_f32_16x16x32_bf16 v[56:59], v[152:155], v[188:191], v[56:59]
	v_mfma_f32_16x16x32_bf16 v[44:47], v[144:147], v[196:199], v[44:47]
	v_mfma_f32_16x16x32_bf16 v[40:43], v[152:155], v[196:199], v[40:43]
	v_mfma_f32_16x16x32_bf16 v[28:31], v[144:147], v[204:207], v[28:31]
	v_mfma_f32_16x16x32_bf16 v[24:27], v[152:155], v[204:207], v[24:27]
	v_mfma_f32_16x16x32_bf16 v[12:15], v[144:147], v[212:215], v[12:15]
	v_mfma_f32_16x16x32_bf16 v[8:11], v[152:155], v[212:215], v[8:11]
	s_nop 0
	s_nop 0
	v_mfma_f32_16x16x32_bf16 v[52:55], v[156:159], v[184:187], v[52:55]
	v_mfma_f32_16x16x32_bf16 v[48:51], v[176:179], v[184:187], v[48:51]
	v_mfma_f32_16x16x32_bf16 v[36:39], v[156:159], v[192:195], v[36:39]
	v_mfma_f32_16x16x32_bf16 v[32:35], v[176:179], v[192:195], v[32:35]
	v_mfma_f32_16x16x32_bf16 v[20:23], v[156:159], v[200:203], v[20:23]
	v_mfma_f32_16x16x32_bf16 v[16:19], v[176:179], v[200:203], v[16:19]
	v_mfma_f32_16x16x32_bf16 v[4:7], v[156:159], v[208:211], v[4:7]
	v_mfma_f32_16x16x32_bf16 v[0:3], v[176:179], v[208:211], v[0:3]
	v_mfma_f32_16x16x32_bf16 v[52:55], v[172:175], v[188:191], v[52:55]
	v_mfma_f32_16x16x32_bf16 v[48:51], v[180:183], v[188:191], v[48:51]
	v_mfma_f32_16x16x32_bf16 v[36:39], v[172:175], v[196:199], v[36:39]
	v_mfma_f32_16x16x32_bf16 v[32:35], v[180:183], v[196:199], v[32:35]
	v_mfma_f32_16x16x32_bf16 v[20:23], v[172:175], v[204:207], v[20:23]
	v_mfma_f32_16x16x32_bf16 v[16:19], v[180:183], v[204:207], v[16:19]
	v_mfma_f32_16x16x32_bf16 v[4:7], v[172:175], v[212:215], v[4:7]
	v_mfma_f32_16x16x32_bf16 v[0:3], v[180:183], v[212:215], v[0:3]
	s_nop 0
	s_barrier
	s_add_i32 s52, s52, 2
	s_add_u32 s0, s0, 0x100
	s_addc_u32 s1, s1, 0
	s_add_u32 s50, s50, 0x100
	s_addc_u32 s51, s51, 0
	s_cmpk_gt_u32 s52, 0x55
	s_cbranch_scc0 .LBB0_1449
	s_setprio 0
	s_and_b64 vcc, exec, s[10:11]
	s_cbranch_vccz .LBB0_1452
	s_barrier
